# LN2: gamma/beta loads batched 8 pairs at a time (no per-pair store drain) and the x_sample refill loads issued together
# speedup vs baseline: 1.0224x; 1.0005x over previous
; __device__ __forceinline__ float bflo(unsigned w) { return __uint_as_float(w << 16); }
; __device__ __forceinline__ float bfhi(unsigned w) { return __uint_as_float(w & 0xffff0000u); }
; __global__ void __launch_bounds__(NWAVES * 64, 2) mega_fwd(Args args) {
;     ...
;             const float* xr = xin + (size_t)row * DM; const bf16* mr = MP + (size_t)row * DM; f32x4 v[16]; float s = 0.f;
; #pragma unroll
;             for (int j = 0; j < 16; ++j) { const f32x4 xv = *(const f32x4*)(xr + 4 * lane + 256 * j); const v2u m = *(const v2u*)(mr + 4 * lane + 256 * j);
;                 v[j] = xv * DEEP_ALPHA + (f32x4){bflo(m[0]), bfhi(m[0]), bflo(m[1]), bfhi(m[1])}; s += (v[j][0] + v[j][1]) + (v[j][2] + v[j][3]); }
;             const float mean = wave_sum(s, lane) * (1.0f / DM); float q = 0.f;
.LBB0_506:
	s_nop 1
	v_add_co_u32_e32 v76, vcc, 0xffffd000, v64
	v_lshl_add_u64 v[66:67], s[78:79], 0, v[62:63]
	s_nop 0
	v_addc_co_u32_e32 v77, vcc, -1, v65, vcc
	v_add_co_u32_e32 v0, vcc, 0x38e00000, v66
	global_load_dwordx4 v[142:145], v[76:77], off offset:-3072
	s_nop 0
	v_addc_co_u32_e32 v1, vcc, 0, v67, vcc
	global_load_dwordx2 v[146:147], v[0:1], off
	s_movk_i32 s5, 0xe000
	v_add_co_u32_e32 v96, vcc, s5, v64
	s_movk_i32 s5, 0xf000
	s_nop 0
	v_addc_co_u32_e32 v97, vcc, -1, v65, vcc
	v_add_co_u32_e32 v106, vcc, s5, v64
	s_mov_b32 s5, 0x38e01000
	s_nop 0
	v_addc_co_u32_e32 v107, vcc, -1, v65, vcc
	v_add_co_u32_e32 v124, vcc, s5, v66
	s_nop 1
	v_addc_co_u32_e32 v125, vcc, 0, v67, vcc
	global_load_dwordx4 v[148:151], v[76:77], off offset:-2048
	global_load_dwordx2 v[152:153], v[0:1], off offset:512
	s_nop 0
	global_load_dwordx4 v[154:157], v[76:77], off offset:-1024
	global_load_dwordx2 v[158:159], v[0:1], off offset:1024
	global_load_dwordx4 v[160:163], v[76:77], off
	s_nop 0
	global_load_dwordx2 v[164:165], v[0:1], off offset:1536
	s_nop 0
	global_load_dwordx4 v[166:169], v[96:97], off offset:-3072
	global_load_dwordx2 v[170:171], v[0:1], off offset:2048
	s_nop 0
	global_load_dwordx4 v[172:175], v[96:97], off offset:-2048
	global_load_dwordx2 v[176:177], v[0:1], off offset:2560
	global_load_dwordx4 v[178:181], v[96:97], off offset:-1024
	global_load_dwordx2 v[182:183], v[0:1], off offset:3072
	global_load_dwordx4 v[184:187], v[96:97], off
	s_nop 0
	global_load_dwordx2 v[188:189], v[0:1], off offset:3584
	global_load_dwordx2 v[190:191], v[124:125], off
	global_load_dwordx4 v[194:197], v[106:107], off offset:-3072
	global_load_dwordx4 v[198:201], v[106:107], off offset:-2048
	global_load_dwordx2 v[202:203], v[124:125], off offset:512
	s_nop 0
	s_nop 0
	global_load_dwordx4 v[204:207], v[106:107], off offset:-1024
	global_load_dwordx2 v[208:209], v[124:125], off offset:1024
	s_nop 0
	global_load_dwordx4 v[210:213], v[64:65], off offset:-4096
	global_load_dwordx2 v[214:215], v[124:125], off offset:1536
	global_load_dwordx4 v[220:223], v[64:65], off offset:-3072
	global_load_dwordx2 v[224:225], v[124:125], off offset:2048
	s_nop 0
	s_nop 0
	global_load_dwordx4 v[226:229], v[64:65], off offset:-2048
	global_load_dwordx2 v[230:231], v[124:125], off offset:2560
	s_nop 0
	global_load_dwordx4 v[232:235], v[64:65], off offset:-1024
	global_load_dwordx2 v[236:237], v[124:125], off offset:3072
	global_load_dwordx4 v[238:241], v[64:65], off
	s_nop 0
	global_load_dwordx2 v[242:243], v[124:125], off offset:3584
	s_mov_b32 s5, 0xda24260
	s_nop 1
	s_waitcnt vmcnt(30)
	v_lshlrev_b32_e32 v68, 16, v146
	v_and_b32_e32 v69, 0xffff0000, v146
	v_lshlrev_b32_e32 v6, 16, v147
	v_and_b32_e32 v7, 0xffff0000, v147
	v_pk_fma_f32 v[4:5], v[144:145], s[88:89], v[6:7] op_sel_hi:[1,0,1]
	v_pk_fma_f32 v[6:7], v[142:143], s[88:89], v[68:69] op_sel_hi:[1,0,1]
	v_mov_b32_e32 v69, v5
	v_pk_mov_b32 v[2:3], v[6:7], v[4:5] op_sel:[1,0]
	v_mov_b32_e32 v68, v6
	v_pk_add_f32 v[2:3], v[2:3], v[68:69]
	s_nop 1
	v_add_f32_e32 v2, v2, v3
	v_add_f32_e32 v2, 0, v2
	s_waitcnt vmcnt(28)
	v_lshlrev_b32_e32 v74, 16, v152
	v_and_b32_e32 v75, 0xffff0000, v152
	v_lshlrev_b32_e32 v72, 16, v153
	v_and_b32_e32 v73, 0xffff0000, v153
	v_pk_fma_f32 v[72:73], v[150:151], s[88:89], v[72:73] op_sel_hi:[1,0,1]
	v_pk_fma_f32 v[74:75], v[148:149], s[88:89], v[74:75] op_sel_hi:[1,0,1]
	v_mov_b32_e32 v71, v73
	v_pk_mov_b32 v[68:69], v[74:75], v[72:73] op_sel:[1,0]
	v_mov_b32_e32 v70, v74
	v_pk_add_f32 v[68:69], v[68:69], v[70:71]
	s_nop 0
	v_pk_add_f32 v[84:85], v[68:69], v[68:69] op_sel:[0,1] op_sel_hi:[1,0]
	s_nop 1
	s_waitcnt vmcnt(26)
	v_lshlrev_b32_e32 v80, 16, v158
	v_and_b32_e32 v81, 0xffff0000, v158
	v_lshlrev_b32_e32 v78, 16, v159
	v_and_b32_e32 v79, 0xffff0000, v159
	v_pk_fma_f32 v[78:79], v[156:157], s[88:89], v[78:79] op_sel_hi:[1,0,1]
	v_pk_fma_f32 v[82:83], v[154:155], s[88:89], v[80:81] op_sel_hi:[1,0,1]
	s_nop 1
	v_add_f32_e32 v86, v82, v83
	v_add_f32_e32 v88, v78, v79
	s_waitcnt vmcnt(24)
	v_lshlrev_b32_e32 v80, 16, v164
	v_and_b32_e32 v81, 0xffff0000, v164
	v_lshlrev_b32_e32 v76, 16, v165
	v_and_b32_e32 v77, 0xffff0000, v165
	v_pk_fma_f32 v[76:77], v[162:163], s[88:89], v[76:77] op_sel_hi:[1,0,1]
	v_pk_fma_f32 v[80:81], v[160:161], s[88:89], v[80:81] op_sel_hi:[1,0,1]
	v_mov_b32_e32 v87, v76
	v_mov_b32_e32 v3, v80
	v_mov_b32_e32 v85, v81
	v_mov_b32_e32 v89, v77
	v_pk_add_f32 v[2:3], v[2:3], v[84:85]
	v_pk_add_f32 v[68:69], v[86:87], v[88:89]
	s_nop 0
	v_pk_add_f32 v[2:3], v[2:3], v[68:69]
	s_nop 1
	v_pk_add_f32 v[2:3], v[2:3], v[2:3] op_sel:[0,1] op_sel_hi:[1,0]
	s_waitcnt vmcnt(22)
	v_lshlrev_b32_e32 v86, 16, v170
	v_and_b32_e32 v87, 0xffff0000, v170
	v_lshlrev_b32_e32 v84, 16, v171
	v_and_b32_e32 v85, 0xffff0000, v171
	v_pk_fma_f32 v[88:89], v[168:169], s[88:89], v[84:85] op_sel_hi:[1,0,1]
	v_pk_fma_f32 v[90:91], v[166:167], s[88:89], v[86:87] op_sel_hi:[1,0,1]
	v_mov_b32_e32 v71, v89
	v_pk_mov_b32 v[68:69], v[90:91], v[88:89] op_sel:[1,0]
	v_mov_b32_e32 v70, v90
	v_pk_add_f32 v[68:69], v[68:69], v[70:71]
	s_nop 0
	v_pk_add_f32 v[98:99], v[68:69], v[68:69] op_sel:[0,1] op_sel_hi:[1,0]
	s_nop 1
	s_waitcnt vmcnt(20)
	v_lshlrev_b32_e32 v86, 16, v176
	v_and_b32_e32 v87, 0xffff0000, v176
	v_lshlrev_b32_e32 v84, 16, v177
	v_and_b32_e32 v85, 0xffff0000, v177
	v_pk_fma_f32 v[92:93], v[174:175], s[88:89], v[84:85] op_sel_hi:[1,0,1]
	v_pk_fma_f32 v[94:95], v[172:173], s[88:89], v[86:87] op_sel_hi:[1,0,1]
	s_nop 1
	v_add_f32_e32 v100, v94, v95
	v_add_f32_e32 v102, v92, v93
	s_waitcnt vmcnt(18)
; __device__ __forceinline__ float bflo(unsigned w) { return __uint_as_float(w << 16); }
; __device__ __forceinline__ float bfhi(unsigned w) { return __uint_as_float(w & 0xffff0000u); }
; __global__ void __launch_bounds__(NWAVES * 64, 2) mega_fwd(Args args) {
;     ...
;             for (int j = 0; j < 16; ++j) { const f32x4 xv = *(const f32x4*)(xr + 4 * lane + 256 * j); const v2u m = *(const v2u*)(mr + 4 * lane + 256 * j);
;                 v[j] = xv * DEEP_ALPHA + (f32x4){bflo(m[0]), bfhi(m[0]), bflo(m[1]), bfhi(m[1])}; s += (v[j][0] + v[j][1]) + (v[j][2] + v[j][3]); }
;             const float mean = wave_sum(s, lane) * (1.0f / DM); float q = 0.f;
	v_lshlrev_b32_e32 v86, 16, v182
	v_and_b32_e32 v87, 0xffff0000, v182
	v_pk_fma_f32 v[86:87], v[178:179], s[88:89], v[86:87] op_sel_hi:[1,0,1]
	v_lshlrev_b32_e32 v84, 16, v183
	v_mov_b32_e32 v3, v86
	v_mov_b32_e32 v99, v87
	v_pk_add_f32 v[2:3], v[2:3], v[98:99]
	s_nop 1
	v_and_b32_e32 v85, 0xffff0000, v183
	v_pk_fma_f32 v[84:85], v[180:181], s[88:89], v[84:85] op_sel_hi:[1,0,1]
	s_waitcnt vmcnt(16)
	v_lshlrev_b32_e32 v70, 16, v188
	v_mov_b32_e32 v101, v84
	v_mov_b32_e32 v103, v85
	v_pk_add_f32 v[68:69], v[100:101], v[102:103]
	v_and_b32_e32 v71, 0xffff0000, v188
	v_lshlrev_b32_e32 v0, 16, v189
	v_and_b32_e32 v1, 0xffff0000, v189
	v_pk_add_f32 v[2:3], v[2:3], v[68:69]
	v_pk_fma_f32 v[68:69], v[186:187], s[88:89], v[0:1] op_sel_hi:[1,0,1]
	v_pk_fma_f32 v[70:71], v[184:185], s[88:89], v[70:71] op_sel_hi:[1,0,1]
	v_mov_b32_e32 v97, v69
	v_pk_mov_b32 v[0:1], v[70:71], v[68:69] op_sel:[1,0]
	v_mov_b32_e32 v96, v70
	v_pk_add_f32 v[0:1], v[0:1], v[96:97]
	s_nop 1
	v_pk_add_f32 v[2:3], v[2:3], v[2:3] op_sel:[0,1] op_sel_hi:[1,0]
	v_pk_add_f32 v[0:1], v[0:1], v[0:1] op_sel:[0,1] op_sel_hi:[1,0]
	s_waitcnt vmcnt(15)
	v_lshlrev_b32_e32 v102, 16, v190
	v_and_b32_e32 v103, 0xffff0000, v190
	v_lshlrev_b32_e32 v96, 16, v191
	v_and_b32_e32 v97, 0xffff0000, v191
	s_waitcnt vmcnt(14)
	v_pk_fma_f32 v[96:97], v[196:197], s[88:89], v[96:97] op_sel_hi:[1,0,1]
	v_pk_fma_f32 v[98:99], v[194:195], s[88:89], v[102:103] op_sel_hi:[1,0,1]
	s_nop 1
	v_add_f32_e32 v108, v98, v99
	v_add_f32_e32 v110, v96, v97
	s_waitcnt vmcnt(12)
	v_lshlrev_b32_e32 v112, 16, v202
	v_and_b32_e32 v113, 0xffff0000, v202
	v_lshlrev_b32_e32 v100, 16, v203
	v_and_b32_e32 v101, 0xffff0000, v203
	v_pk_fma_f32 v[100:101], v[200:201], s[88:89], v[100:101] op_sel_hi:[1,0,1]
	v_pk_fma_f32 v[102:103], v[198:199], s[88:89], v[112:113] op_sel_hi:[1,0,1]
	v_mov_b32_e32 v109, v100
	v_mov_b32_e32 v3, v102
	v_mov_b32_e32 v1, v103
	v_mov_b32_e32 v111, v101
	v_pk_add_f32 v[0:1], v[2:3], v[0:1]
	v_pk_add_f32 v[2:3], v[108:109], v[110:111]
	s_nop 0
	v_pk_add_f32 v[0:1], v[0:1], v[2:3]
	s_nop 0
	v_pk_add_f32 v[116:117], v[0:1], v[0:1] op_sel:[0,1] op_sel_hi:[1,0]
	s_nop 1
	s_waitcnt vmcnt(10)
	v_lshlrev_b32_e32 v106, 16, v208
	v_and_b32_e32 v107, 0xffff0000, v208
	v_lshlrev_b32_e32 v104, 16, v209
	v_and_b32_e32 v105, 0xffff0000, v209
	v_pk_fma_f32 v[104:105], v[206:207], s[88:89], v[104:105] op_sel_hi:[1,0,1]
	v_pk_fma_f32 v[106:107], v[204:205], s[88:89], v[106:107] op_sel_hi:[1,0,1]
	v_mov_b32_e32 v3, v105
	v_pk_mov_b32 v[0:1], v[106:107], v[104:105] op_sel:[1,0]
	v_mov_b32_e32 v2, v106
	v_pk_add_f32 v[0:1], v[0:1], v[2:3]
	s_nop 0
	v_pk_add_f32 v[118:119], v[0:1], v[0:1] op_sel:[0,1] op_sel_hi:[1,0]
	s_nop 1
	s_waitcnt vmcnt(8)
	v_lshlrev_b32_e32 v110, 16, v214
	v_and_b32_e32 v111, 0xffff0000, v214
	v_lshlrev_b32_e32 v108, 16, v215
	v_and_b32_e32 v109, 0xffff0000, v215
	v_pk_fma_f32 v[108:109], v[212:213], s[88:89], v[108:109] op_sel_hi:[1,0,1]
	v_pk_fma_f32 v[110:111], v[210:211], s[88:89], v[110:111] op_sel_hi:[1,0,1]
	s_nop 1
	v_add_f32_e32 v120, v110, v111
	v_add_f32_e32 v122, v108, v109
	s_waitcnt vmcnt(6)
	v_lshlrev_b32_e32 v114, 16, v224
	v_and_b32_e32 v115, 0xffff0000, v224
	v_lshlrev_b32_e32 v112, 16, v225
	v_and_b32_e32 v113, 0xffff0000, v225
	v_pk_fma_f32 v[112:113], v[222:223], s[88:89], v[112:113] op_sel_hi:[1,0,1]
	v_pk_fma_f32 v[114:115], v[220:221], s[88:89], v[114:115] op_sel_hi:[1,0,1]
	v_mov_b32_e32 v121, v112
	v_mov_b32_e32 v117, v114
	v_mov_b32_e32 v119, v115
	v_mov_b32_e32 v123, v113
	v_pk_add_f32 v[0:1], v[116:117], v[118:119]
	v_pk_add_f32 v[2:3], v[120:121], v[122:123]
	s_nop 0
	v_pk_add_f32 v[0:1], v[0:1], v[2:3]
	s_nop 0
	v_pk_add_f32 v[128:129], v[0:1], v[0:1] op_sel:[0,1] op_sel_hi:[1,0]
	s_nop 1
	s_waitcnt vmcnt(4)
	v_lshlrev_b32_e32 v118, 16, v230
	v_and_b32_e32 v119, 0xffff0000, v230
	v_lshlrev_b32_e32 v116, 16, v231
	v_and_b32_e32 v117, 0xffff0000, v231
	v_pk_fma_f32 v[116:117], v[228:229], s[88:89], v[116:117] op_sel_hi:[1,0,1]
	v_pk_fma_f32 v[118:119], v[226:227], s[88:89], v[118:119] op_sel_hi:[1,0,1]
	v_mov_b32_e32 v3, v117
	v_pk_mov_b32 v[0:1], v[118:119], v[116:117] op_sel:[1,0]
	v_mov_b32_e32 v2, v118
	v_pk_add_f32 v[0:1], v[0:1], v[2:3]
	s_nop 0
	v_pk_add_f32 v[130:131], v[0:1], v[0:1] op_sel:[0,1] op_sel_hi:[1,0]
	s_nop 1
	s_waitcnt vmcnt(2)
	v_lshlrev_b32_e32 v122, 16, v236
	v_and_b32_e32 v123, 0xffff0000, v236
	v_lshlrev_b32_e32 v120, 16, v237
	v_and_b32_e32 v121, 0xffff0000, v237
	v_pk_fma_f32 v[120:121], v[234:235], s[88:89], v[120:121] op_sel_hi:[1,0,1]
	v_pk_fma_f32 v[122:123], v[232:233], s[88:89], v[122:123] op_sel_hi:[1,0,1]
	s_nop 1
	v_add_f32_e32 v132, v122, v123
	v_add_f32_e32 v134, v120, v121
	s_waitcnt vmcnt(0)
	v_lshlrev_b32_e32 v126, 16, v242
	v_and_b32_e32 v127, 0xffff0000, v242
	v_lshlrev_b32_e32 v124, 16, v243
	v_and_b32_e32 v125, 0xffff0000, v243
	v_pk_fma_f32 v[124:125], v[240:241], s[88:89], v[124:125] op_sel_hi:[1,0,1]
	v_pk_fma_f32 v[126:127], v[238:239], s[88:89], v[126:127] op_sel_hi:[1,0,1]
	v_mov_b32_e32 v133, v124
	v_mov_b32_e32 v129, v126
	v_mov_b32_e32 v131, v127
	v_mov_b32_e32 v135, v125
	v_pk_add_f32 v[0:1], v[128:129], v[130:131]
	v_pk_add_f32 v[2:3], v[132:133], v[134:135]
	s_nop 0
	v_pk_add_f32 v[0:1], v[0:1], v[2:3]
	s_nop 0
	v_add_f32_e32 v0, v0, v1
	ds_bpermute_b32 v1, v136, v0
	s_waitcnt lgkmcnt(0)
	v_add_f32_e32 v0, v0, v1
	ds_bpermute_b32 v1, v137, v0
	s_waitcnt lgkmcnt(0)
	v_add_f32_e32 v0, v0, v1
	ds_bpermute_b32 v1, v138, v0
	s_waitcnt lgkmcnt(0)
	v_add_f32_e32 v0, v0, v1
	ds_bpermute_b32 v1, v139, v0
	s_waitcnt lgkmcnt(0)
	v_add_f32_e32 v0, v0, v1
	ds_bpermute_b32 v1, v140, v0
	s_waitcnt lgkmcnt(0)
; __global__ void __launch_bounds__(NWAVES * 64, 2) mega_fwd(Args args) {
;     ...
;             const float mean = wave_sum(s, lane) * (1.0f / DM); float q = 0.f;
; #pragma unroll
;             for (int j = 0; j < 16; ++j) { v[j] = v[j] - mean; q += (v[j][0] * v[j][0] + v[j][1] * v[j][1]) + (v[j][2] * v[j][2] + v[j][3] * v[j][3]); }
	v_add_f32_e32 v0, v0, v1
	ds_bpermute_b32 v1, v141, v0
	s_waitcnt lgkmcnt(0)
	v_add_f32_e32 v132, v0, v1
	v_fmamk_f32 v7, v132, 0xb9800000, v7
	v_fmac_f32_e32 v6, 0xb9800000, v132
	v_fmamk_f32 v5, v132, 0xb9800000, v5
	v_fmac_f32_e32 v4, 0xb9800000, v132
	v_pk_mul_f32 v[0:1], v[4:5], v[4:5]
	v_pk_mul_f32 v[2:3], v[6:7], v[6:7]
	v_fmamk_f32 v75, v132, 0xb9800000, v75
	v_pk_mov_b32 v[128:129], v[2:3], v[0:1] op_sel:[1,0]
	v_mov_b32_e32 v3, v1
	v_fmac_f32_e32 v74, 0xb9800000, v132
	v_fmamk_f32 v73, v132, 0xb9800000, v73
	v_fmac_f32_e32 v72, 0xb9800000, v132
	v_pk_add_f32 v[0:1], v[128:129], v[2:3]
	v_pk_mul_f32 v[2:3], v[72:73], v[72:73]
	v_pk_mul_f32 v[128:129], v[74:75], v[74:75]
	v_fmamk_f32 v81, v132, 0xb9800000, v81
	v_pk_mov_b32 v[130:131], v[128:129], v[2:3] op_sel:[1,0]
	v_mov_b32_e32 v129, v3
	v_pk_add_f32 v[2:3], v[130:131], v[128:129]
	v_fmac_f32_e32 v80, 0xb9800000, v132
	v_mul_f32_e32 v128, v80, v80
	v_mul_f32_e32 v129, v81, v81
	v_pk_add_f32 v[0:1], v[0:1], v[0:1] op_sel:[0,1] op_sel_hi:[1,0]
	v_pk_add_f32 v[2:3], v[2:3], v[2:3] op_sel:[0,1] op_sel_hi:[1,0]
	v_fmamk_f32 v83, v132, 0xb9800000, v83
	v_fmamk_f32 v79, v132, 0xb9800000, v79
	v_mov_b32_e32 v1, v128
	v_mov_b32_e32 v3, v129
	v_fmac_f32_e32 v82, 0xb9800000, v132
	v_fmac_f32_e32 v78, 0xb9800000, v132
	v_fmamk_f32 v77, v132, 0xb9800000, v77
	v_fmac_f32_e32 v76, 0xb9800000, v132
	v_pk_add_f32 v[0:1], v[0:1], v[2:3]
	v_mul_f32_e32 v2, v83, v83
	v_mul_f32_e32 v128, v79, v79
	v_mul_f32_e32 v130, v76, v76
	v_mul_f32_e32 v131, v77, v77
	v_pk_fma_f32 v[2:3], v[82:83], v[82:83], v[2:3] op_sel_hi:[1,1,0]
	v_pk_fma_f32 v[128:129], v[78:79], v[78:79], v[128:129] op_sel_hi:[1,1,0]
	v_mov_b32_e32 v3, v130
	v_mov_b32_e32 v129, v131
	v_pk_add_f32 v[2:3], v[2:3], v[128:129]
	v_fmamk_f32 v91, v132, 0xb9800000, v91
	v_fmac_f32_e32 v90, 0xb9800000, v132
	v_fmamk_f32 v89, v132, 0xb9800000, v89
	v_fmac_f32_e32 v88, 0xb9800000, v132
	v_pk_add_f32 v[0:1], v[0:1], v[2:3]
	v_pk_mul_f32 v[2:3], v[88:89], v[88:89]
	v_pk_mul_f32 v[128:129], v[90:91], v[90:91]
	v_fmamk_f32 v87, v132, 0xb9800000, v87
	v_pk_mov_b32 v[130:131], v[128:129], v[2:3] op_sel:[1,0]
	v_mov_b32_e32 v129, v3
	v_pk_add_f32 v[2:3], v[130:131], v[128:129]
	v_fmac_f32_e32 v86, 0xb9800000, v132
	v_mul_f32_e32 v128, v86, v86
	v_mul_f32_e32 v129, v87, v87
	v_pk_add_f32 v[0:1], v[0:1], v[0:1] op_sel:[0,1] op_sel_hi:[1,0]
	v_pk_add_f32 v[2:3], v[2:3], v[2:3] op_sel:[0,1] op_sel_hi:[1,0]
	v_fmamk_f32 v95, v132, 0xb9800000, v95
	v_fmamk_f32 v93, v132, 0xb9800000, v93
	v_mov_b32_e32 v1, v128
	v_mov_b32_e32 v3, v129
	v_fmac_f32_e32 v94, 0xb9800000, v132
	v_fmac_f32_e32 v92, 0xb9800000, v132
	v_fmamk_f32 v85, v132, 0xb9800000, v85
	v_fmac_f32_e32 v84, 0xb9800000, v132
	v_pk_add_f32 v[0:1], v[0:1], v[2:3]
	v_mul_f32_e32 v2, v95, v95
	v_mul_f32_e32 v128, v93, v93
	v_mul_f32_e32 v130, v84, v84
	v_mul_f32_e32 v131, v85, v85
	v_pk_fma_f32 v[2:3], v[94:95], v[94:95], v[2:3] op_sel_hi:[1,1,0]
	v_pk_fma_f32 v[128:129], v[92:93], v[92:93], v[128:129] op_sel_hi:[1,1,0]
	v_mov_b32_e32 v3, v130
	v_mov_b32_e32 v129, v131
	v_pk_add_f32 v[2:3], v[2:3], v[128:129]
	v_fmamk_f32 v71, v132, 0xb9800000, v71
	v_fmac_f32_e32 v70, 0xb9800000, v132
	v_fmamk_f32 v69, v132, 0xb9800000, v69
	v_fmac_f32_e32 v68, 0xb9800000, v132
	v_pk_add_f32 v[0:1], v[0:1], v[2:3]
	v_pk_mul_f32 v[2:3], v[68:69], v[68:69]
	v_pk_mul_f32 v[128:129], v[70:71], v[70:71]
	v_fmamk_f32 v103, v132, 0xb9800000, v103
	v_pk_mov_b32 v[130:131], v[128:129], v[2:3] op_sel:[1,0]
	v_mov_b32_e32 v129, v3
	v_pk_add_f32 v[2:3], v[130:131], v[128:129]
	v_fmac_f32_e32 v102, 0xb9800000, v132
	v_mul_f32_e32 v128, v102, v102
	v_mul_f32_e32 v129, v103, v103
	v_pk_add_f32 v[0:1], v[0:1], v[0:1] op_sel:[0,1] op_sel_hi:[1,0]
	v_pk_add_f32 v[2:3], v[2:3], v[2:3] op_sel:[0,1] op_sel_hi:[1,0]
	v_fmamk_f32 v99, v132, 0xb9800000, v99
	v_fmamk_f32 v97, v132, 0xb9800000, v97
	v_mov_b32_e32 v1, v128
	v_mov_b32_e32 v3, v129
	v_fmac_f32_e32 v98, 0xb9800000, v132
	v_fmac_f32_e32 v96, 0xb9800000, v132
	v_fmamk_f32 v101, v132, 0xb9800000, v101
	v_fmac_f32_e32 v100, 0xb9800000, v132
	v_pk_add_f32 v[0:1], v[0:1], v[2:3]
	v_mul_f32_e32 v2, v99, v99
	v_mul_f32_e32 v128, v97, v97
	v_mul_f32_e32 v130, v100, v100
	v_mul_f32_e32 v131, v101, v101
	v_pk_fma_f32 v[2:3], v[98:99], v[98:99], v[2:3] op_sel_hi:[1,1,0]
	v_pk_fma_f32 v[128:129], v[96:97], v[96:97], v[128:129] op_sel_hi:[1,1,0]
	v_mov_b32_e32 v3, v130
	v_mov_b32_e32 v129, v131
	v_pk_add_f32 v[2:3], v[2:3], v[128:129]
	v_fmamk_f32 v107, v132, 0xb9800000, v107
	v_fmac_f32_e32 v106, 0xb9800000, v132
	v_fmamk_f32 v105, v132, 0xb9800000, v105
	v_fmac_f32_e32 v104, 0xb9800000, v132
	v_pk_add_f32 v[0:1], v[0:1], v[2:3]
	v_pk_mul_f32 v[2:3], v[104:105], v[104:105]
	v_pk_mul_f32 v[128:129], v[106:107], v[106:107]
	v_fmamk_f32 v115, v132, 0xb9800000, v115
	v_pk_mov_b32 v[130:131], v[128:129], v[2:3] op_sel:[1,0]
	v_mov_b32_e32 v129, v3
	v_pk_add_f32 v[2:3], v[130:131], v[128:129]
	v_fmac_f32_e32 v114, 0xb9800000, v132
	v_mul_f32_e32 v128, v114, v114
	v_mul_f32_e32 v129, v115, v115
	v_pk_add_f32 v[0:1], v[0:1], v[0:1] op_sel:[0,1] op_sel_hi:[1,0]
	v_pk_add_f32 v[2:3], v[2:3], v[2:3] op_sel:[0,1] op_sel_hi:[1,0]
	v_fmamk_f32 v111, v132, 0xb9800000, v111
	v_fmamk_f32 v109, v132, 0xb9800000, v109
	v_mov_b32_e32 v1, v128
	v_mov_b32_e32 v3, v129
	v_fmac_f32_e32 v110, 0xb9800000, v132
	v_fmac_f32_e32 v108, 0xb9800000, v132
	v_fmamk_f32 v113, v132, 0xb9800000, v113
	v_fmac_f32_e32 v112, 0xb9800000, v132
	v_pk_add_f32 v[0:1], v[0:1], v[2:3]
	v_mul_f32_e32 v2, v111, v111
	v_mul_f32_e32 v128, v109, v109
	v_mul_f32_e32 v130, v112, v112
	v_mul_f32_e32 v131, v113, v113
; __global__ void __launch_bounds__(NWAVES * 64, 2) mega_fwd(Args args) {
;     ...
;             for (int j = 0; j < 16; ++j) { v[j] = v[j] - mean; q += (v[j][0] * v[j][0] + v[j][1] * v[j][1]) + (v[j][2] * v[j][2] + v[j][3] * v[j][3]); }
;             const float rstd = 1.0f / sqrtf(wave_sum(q, lane) * (1.0f / DM) + LN_EPS); float am = 0.f;
; #pragma unroll
;             for (int j = 0; j < 16; ++j) { const f32x4 gg = *(const f32x4*)(ln1_g + 4 * lane + 256 * j), bb = *(const f32x4*)(ln1_b + 4 * lane + 256 * j);
;                 const f32x4 y = v[j] * rstd * gg + bb; v[j] = y; am = fmaxf(fmaxf(am, fmaxf(fabsf(y[0]), fabsf(y[1]))), fmaxf(fabsf(y[2]), fabsf(y[3]))); }
	v_pk_fma_f32 v[2:3], v[110:111], v[110:111], v[2:3] op_sel_hi:[1,1,0]
	v_pk_fma_f32 v[128:129], v[108:109], v[108:109], v[128:129] op_sel_hi:[1,1,0]
	v_mov_b32_e32 v3, v130
	v_mov_b32_e32 v129, v131
	v_pk_add_f32 v[2:3], v[2:3], v[128:129]
	v_fmamk_f32 v119, v132, 0xb9800000, v119
	v_fmac_f32_e32 v118, 0xb9800000, v132
	v_fmamk_f32 v117, v132, 0xb9800000, v117
	v_fmac_f32_e32 v116, 0xb9800000, v132
	v_pk_add_f32 v[0:1], v[0:1], v[2:3]
	v_pk_mul_f32 v[2:3], v[116:117], v[116:117]
	v_pk_mul_f32 v[128:129], v[118:119], v[118:119]
	v_fmamk_f32 v127, v132, 0xb9800000, v127
	v_pk_mov_b32 v[130:131], v[128:129], v[2:3] op_sel:[1,0]
	v_mov_b32_e32 v129, v3
	v_pk_add_f32 v[2:3], v[130:131], v[128:129]
	v_fmac_f32_e32 v126, 0xb9800000, v132
	v_mul_f32_e32 v128, v126, v126
	v_mul_f32_e32 v129, v127, v127
	v_pk_add_f32 v[0:1], v[0:1], v[0:1] op_sel:[0,1] op_sel_hi:[1,0]
	v_pk_add_f32 v[2:3], v[2:3], v[2:3] op_sel:[0,1] op_sel_hi:[1,0]
	v_fmamk_f32 v123, v132, 0xb9800000, v123
	v_fmamk_f32 v121, v132, 0xb9800000, v121
	v_mov_b32_e32 v1, v128
	v_mov_b32_e32 v3, v129
	v_fmac_f32_e32 v122, 0xb9800000, v132
	v_fmac_f32_e32 v120, 0xb9800000, v132
	v_fmamk_f32 v125, v132, 0xb9800000, v125
	v_fmac_f32_e32 v124, 0xb9800000, v132
	v_pk_add_f32 v[0:1], v[0:1], v[2:3]
	v_mul_f32_e32 v2, v123, v123
	v_mul_f32_e32 v128, v121, v121
	v_mul_f32_e32 v130, v124, v124
	v_mul_f32_e32 v131, v125, v125
	v_pk_fma_f32 v[2:3], v[122:123], v[122:123], v[2:3] op_sel_hi:[1,1,0]
	v_pk_fma_f32 v[128:129], v[120:121], v[120:121], v[128:129] op_sel_hi:[1,1,0]
	v_mov_b32_e32 v3, v130
	v_mov_b32_e32 v129, v131
	v_pk_add_f32 v[2:3], v[2:3], v[128:129]
	s_nop 0
	v_pk_add_f32 v[0:1], v[0:1], v[2:3]
	s_nop 0
	v_add_f32_e32 v0, v0, v1
	ds_bpermute_b32 v1, v136, v0
	s_waitcnt lgkmcnt(0)
	v_add_f32_e32 v0, v0, v1
	ds_bpermute_b32 v1, v137, v0
	s_waitcnt lgkmcnt(0)
	v_add_f32_e32 v0, v0, v1
	ds_bpermute_b32 v1, v138, v0
	s_waitcnt lgkmcnt(0)
	v_add_f32_e32 v0, v0, v1
	ds_bpermute_b32 v1, v139, v0
	s_waitcnt lgkmcnt(0)
	v_add_f32_e32 v0, v0, v1
	ds_bpermute_b32 v1, v140, v0
	s_waitcnt lgkmcnt(0)
	v_add_f32_e32 v0, v0, v1
	ds_bpermute_b32 v1, v141, v0
	s_waitcnt lgkmcnt(0)
	v_add_f32_e32 v0, v0, v1
	v_mov_b32_e32 v1, 0x3727c5ac
	v_fmamk_f32 v0, v0, 0x39800000, v1
	v_cmp_gt_f32_e32 vcc, s55, v0
	v_mul_f32_e32 v1, 0x4f800000, v0
	s_nop 0
	v_cndmask_b32_e32 v0, v0, v1, vcc
	v_sqrt_f32_e32 v1, v0
	s_nop 0
	v_add_u32_e32 v2, -1, v1
	v_fma_f32 v3, -v2, v1, v0
	v_cmp_ge_f32_e64 s[42:43], 0, v3
	v_add_u32_e32 v3, 1, v1
	s_nop 0
	v_cndmask_b32_e64 v2, v1, v2, s[42:43]
	v_fma_f32 v1, -v3, v1, v0
	v_cmp_lt_f32_e64 s[42:43], 0, v1
	s_nop 1
	v_cndmask_b32_e64 v1, v2, v3, s[42:43]
	v_mul_f32_e32 v2, 0x37800000, v1
	v_cndmask_b32_e32 v1, v1, v2, vcc
	v_cmp_class_f32_e32 vcc, v0, v216
	s_nop 1
	v_cndmask_b32_e32 v0, v1, v0, vcc
	v_div_scale_f32 v1, s[6:7], v0, v0, 1.0
	v_rcp_f32_e32 v2, v1
	s_nop 0
	v_fma_f32 v3, -v1, v2, 1.0
	v_fmac_f32_e32 v2, v3, v2
	v_div_scale_f32 v3, vcc, 1.0, v0, 1.0
	v_mul_f32_e32 v128, v3, v2
	v_fma_f32 v129, -v1, v128, v3
	v_fmac_f32_e32 v128, v129, v2
	v_fma_f32 v1, -v1, v128, v3
	v_div_fmas_f32 v1, v1, v2, v128
	v_div_fixup_f32 v128, v1, v0, 1.0
	s_nop 1
	global_load_dwordx4 v[142:145], v[8:9], off
	global_load_dwordx4 v[146:149], v[10:11], off
	global_load_dwordx4 v[150:153], v[8:9], off offset:1024
	global_load_dwordx4 v[154:157], v[10:11], off offset:1024
	global_load_dwordx4 v[158:161], v[8:9], off offset:2048
	global_load_dwordx4 v[162:165], v[10:11], off offset:2048
	global_load_dwordx4 v[166:169], v[8:9], off offset:3072
	global_load_dwordx4 v[170:173], v[10:11], off offset:3072
	global_load_dwordx4 v[174:177], v[12:13], off
	global_load_dwordx4 v[178:181], v[14:15], off
	global_load_dwordx4 v[182:185], v[16:17], off
	global_load_dwordx4 v[186:189], v[18:19], off
	global_load_dwordx4 v[194:197], v[20:21], off
	global_load_dwordx4 v[198:201], v[22:23], off
	global_load_dwordx4 v[202:205], v[24:25], off
	global_load_dwordx4 v[206:209], v[26:27], off
	v_pk_mul_f32 v[6:7], v[128:129], v[6:7] op_sel_hi:[0,1]
	v_pk_mul_f32 v[4:5], v[128:129], v[4:5] op_sel_hi:[0,1]
	s_waitcnt vmcnt(14)
	v_pk_fma_f32 v[130:131], v[144:145], v[4:5], v[148:149]
	v_pk_fma_f32 v[132:133], v[142:143], v[6:7], v[146:147]
	v_max_f32_e64 v1, |v130|, |v131|
	v_max_f32_e64 v0, |v132|, |v133|
	v_max3_f32 v129, v0, 0, v1
	s_nop 1
	v_pk_mul_f32 v[74:75], v[128:129], v[74:75] op_sel_hi:[0,1]
	v_pk_mul_f32 v[72:73], v[128:129], v[72:73] op_sel_hi:[0,1]
	s_waitcnt vmcnt(12)
	v_pk_fma_f32 v[72:73], v[152:153], v[72:73], v[156:157]
	v_pk_fma_f32 v[74:75], v[150:151], v[74:75], v[154:155]
	v_max_f32_e64 v1, |v72|, |v73|
	v_max_f32_e64 v0, |v74|, |v75|
	v_max3_f32 v129, v129, v0, v1
	s_nop 1
	v_pk_mul_f32 v[82:83], v[128:129], v[82:83] op_sel_hi:[0,1]
	v_pk_mul_f32 v[78:79], v[128:129], v[78:79] op_sel_hi:[0,1]
	s_waitcnt vmcnt(10)
	v_pk_fma_f32 v[78:79], v[160:161], v[78:79], v[164:165]
	v_pk_fma_f32 v[82:83], v[158:159], v[82:83], v[162:163]
	v_max_f32_e64 v1, |v78|, |v79|
	v_max_f32_e64 v0, |v82|, |v83|
	v_max3_f32 v129, v129, v0, v1
	s_nop 1
	v_pk_mul_f32 v[80:81], v[128:129], v[80:81] op_sel_hi:[0,1]
	v_pk_mul_f32 v[76:77], v[128:129], v[76:77] op_sel_hi:[0,1]
	s_waitcnt vmcnt(8)
	v_pk_fma_f32 v[76:77], v[168:169], v[76:77], v[172:173]
	v_pk_fma_f32 v[80:81], v[166:167], v[80:81], v[170:171]
	v_max_f32_e64 v1, |v76|, |v77|
	v_max_f32_e64 v0, |v80|, |v81|
	v_max3_f32 v129, v129, v0, v1
	s_nop 1
	v_pk_mul_f32 v[90:91], v[128:129], v[90:91] op_sel_hi:[0,1]
	v_pk_mul_f32 v[88:89], v[128:129], v[88:89] op_sel_hi:[0,1]
	s_waitcnt vmcnt(6)
; __global__ void __launch_bounds__(NWAVES * 64, 2) mega_fwd(Args args) {
;     ...
;             for (int j = 0; j < 16; ++j) { const f32x4 gg = *(const f32x4*)(ln1_g + 4 * lane + 256 * j), bb = *(const f32x4*)(ln1_b + 4 * lane + 256 * j);
;                 const f32x4 y = v[j] * rstd * gg + bb; v[j] = y; am = fmaxf(fmaxf(am, fmaxf(fabsf(y[0]), fabsf(y[1]))), fmaxf(fabsf(y[2]), fabsf(y[3]))); }
;             am = fmaxf(wave_max(am, lane), 1e-30f);
;             const float qs = 127.f / am;
;             if (lane == 0) SAq[row] = am * (1.0f / (127.f * 127.f));
	v_pk_fma_f32 v[88:89], v[176:177], v[88:89], v[180:181]
	v_pk_fma_f32 v[90:91], v[174:175], v[90:91], v[178:179]
	v_max_f32_e64 v1, |v88|, |v89|
	v_max_f32_e64 v0, |v90|, |v91|
	v_max3_f32 v129, v129, v0, v1
	s_nop 1
	v_pk_mul_f32 v[94:95], v[128:129], v[94:95] op_sel_hi:[0,1]
	v_pk_mul_f32 v[92:93], v[128:129], v[92:93] op_sel_hi:[0,1]
	s_waitcnt vmcnt(4)
	v_pk_fma_f32 v[92:93], v[184:185], v[92:93], v[188:189]
	v_pk_fma_f32 v[94:95], v[182:183], v[94:95], v[186:187]
	v_max_f32_e64 v1, |v92|, |v93|
	v_max_f32_e64 v0, |v94|, |v95|
	v_max3_f32 v129, v129, v0, v1
	s_nop 1
	v_pk_mul_f32 v[86:87], v[128:129], v[86:87] op_sel_hi:[0,1]
	v_pk_mul_f32 v[84:85], v[128:129], v[84:85] op_sel_hi:[0,1]
	s_waitcnt vmcnt(2)
	v_pk_fma_f32 v[84:85], v[196:197], v[84:85], v[200:201]
	v_pk_fma_f32 v[86:87], v[194:195], v[86:87], v[198:199]
	v_max_f32_e64 v1, |v84|, |v85|
	v_max_f32_e64 v0, |v86|, |v87|
	v_max3_f32 v129, v129, v0, v1
	s_nop 1
	v_pk_mul_f32 v[70:71], v[128:129], v[70:71] op_sel_hi:[0,1]
	v_pk_mul_f32 v[68:69], v[128:129], v[68:69] op_sel_hi:[0,1]
	s_waitcnt vmcnt(0)
	v_pk_fma_f32 v[68:69], v[204:205], v[68:69], v[208:209]
	v_pk_fma_f32 v[70:71], v[202:203], v[70:71], v[206:207]
	v_max_f32_e64 v1, |v68|, |v69|
	v_max_f32_e64 v0, |v70|, |v71|
	v_max3_f32 v129, v129, v0, v1
	s_nop 1
	global_load_dwordx4 v[142:145], v[28:29], off
	global_load_dwordx4 v[146:149], v[30:31], off
	global_load_dwordx4 v[150:153], v[32:33], off
	global_load_dwordx4 v[154:157], v[34:35], off
	global_load_dwordx4 v[158:161], v[36:37], off
	global_load_dwordx4 v[162:165], v[38:39], off
	global_load_dwordx4 v[166:169], v[40:41], off
	global_load_dwordx4 v[170:173], v[42:43], off
	global_load_dwordx4 v[174:177], v[44:45], off
	global_load_dwordx4 v[178:181], v[46:47], off
	global_load_dwordx4 v[182:185], v[48:49], off
	global_load_dwordx4 v[186:189], v[50:51], off
	global_load_dwordx4 v[194:197], v[52:53], off
	global_load_dwordx4 v[198:201], v[54:55], off
	global_load_dwordx4 v[202:205], v[56:57], off
	global_load_dwordx4 v[206:209], v[58:59], off
	v_pk_mul_f32 v[98:99], v[128:129], v[98:99] op_sel_hi:[0,1]
	v_pk_mul_f32 v[96:97], v[128:129], v[96:97] op_sel_hi:[0,1]
	s_waitcnt vmcnt(14)
	v_pk_fma_f32 v[96:97], v[144:145], v[96:97], v[148:149]
	v_pk_fma_f32 v[98:99], v[142:143], v[98:99], v[146:147]
	v_max_f32_e64 v1, |v96|, |v97|
	v_max_f32_e64 v0, |v98|, |v99|
	v_max3_f32 v129, v129, v0, v1
	s_nop 1
	v_pk_mul_f32 v[102:103], v[128:129], v[102:103] op_sel_hi:[0,1]
	v_pk_mul_f32 v[100:101], v[128:129], v[100:101] op_sel_hi:[0,1]
	s_waitcnt vmcnt(12)
	v_pk_fma_f32 v[100:101], v[152:153], v[100:101], v[156:157]
	v_pk_fma_f32 v[102:103], v[150:151], v[102:103], v[154:155]
	v_max_f32_e64 v1, |v100|, |v101|
	v_max_f32_e64 v0, |v102|, |v103|
	v_max3_f32 v129, v129, v0, v1
	s_nop 1
	v_pk_mul_f32 v[106:107], v[128:129], v[106:107] op_sel_hi:[0,1]
	v_pk_mul_f32 v[104:105], v[128:129], v[104:105] op_sel_hi:[0,1]
	s_waitcnt vmcnt(10)
	v_pk_fma_f32 v[104:105], v[160:161], v[104:105], v[164:165]
	v_pk_fma_f32 v[106:107], v[158:159], v[106:107], v[162:163]
	v_max_f32_e64 v1, |v104|, |v105|
	v_max_f32_e64 v0, |v106|, |v107|
	v_max3_f32 v129, v129, v0, v1
	s_nop 1
	v_pk_mul_f32 v[110:111], v[128:129], v[110:111] op_sel_hi:[0,1]
	v_pk_mul_f32 v[108:109], v[128:129], v[108:109] op_sel_hi:[0,1]
	s_waitcnt vmcnt(8)
	v_pk_fma_f32 v[108:109], v[168:169], v[108:109], v[172:173]
	v_pk_fma_f32 v[110:111], v[166:167], v[110:111], v[170:171]
	v_max_f32_e64 v1, |v108|, |v109|
	v_max_f32_e64 v0, |v110|, |v111|
	v_max3_f32 v129, v129, v0, v1
	s_nop 1
	v_pk_mul_f32 v[114:115], v[128:129], v[114:115] op_sel_hi:[0,1]
	v_pk_mul_f32 v[112:113], v[128:129], v[112:113] op_sel_hi:[0,1]
	s_waitcnt vmcnt(6)
	v_pk_fma_f32 v[112:113], v[176:177], v[112:113], v[180:181]
	v_pk_fma_f32 v[114:115], v[174:175], v[114:115], v[178:179]
	v_max_f32_e64 v1, |v112|, |v113|
	v_max_f32_e64 v0, |v114|, |v115|
	v_max3_f32 v129, v129, v0, v1
	s_nop 1
	v_pk_mul_f32 v[118:119], v[128:129], v[118:119] op_sel_hi:[0,1]
	v_pk_mul_f32 v[116:117], v[128:129], v[116:117] op_sel_hi:[0,1]
	s_waitcnt vmcnt(4)
	v_pk_fma_f32 v[116:117], v[184:185], v[116:117], v[188:189]
	v_pk_fma_f32 v[118:119], v[182:183], v[118:119], v[186:187]
	v_max_f32_e64 v1, |v116|, |v117|
	v_max_f32_e64 v0, |v118|, |v119|
	v_max3_f32 v129, v129, v0, v1
	s_nop 1
	v_pk_mul_f32 v[122:123], v[128:129], v[122:123] op_sel_hi:[0,1]
	v_pk_mul_f32 v[120:121], v[128:129], v[120:121] op_sel_hi:[0,1]
	s_waitcnt vmcnt(2)
	v_pk_fma_f32 v[120:121], v[196:197], v[120:121], v[200:201]
	v_pk_fma_f32 v[122:123], v[194:195], v[122:123], v[198:199]
	v_max_f32_e64 v1, |v120|, |v121|
	v_max_f32_e64 v0, |v122|, |v123|
	v_max3_f32 v129, v129, v0, v1
	s_nop 1
	v_pk_mul_f32 v[126:127], v[128:129], v[126:127] op_sel_hi:[0,1]
	v_pk_mul_f32 v[124:125], v[128:129], v[124:125] op_sel_hi:[0,1]
	s_waitcnt vmcnt(0)
	v_pk_fma_f32 v[2:3], v[204:205], v[124:125], v[208:209]
	v_pk_fma_f32 v[0:1], v[202:203], v[126:127], v[206:207]
	v_max_f32_e64 v5, |v2|, |v3|
	v_max_f32_e64 v4, |v0|, |v1|
	v_max3_f32 v4, v129, v4, v5
	ds_bpermute_b32 v5, v136, v4
	s_waitcnt lgkmcnt(0)
	v_max_f32_e32 v5, v5, v5
	v_max_f32_e32 v4, v4, v5
	ds_bpermute_b32 v5, v137, v4
	s_waitcnt lgkmcnt(0)
	v_max_f32_e32 v5, v5, v5
	v_max_f32_e32 v4, v4, v5
	ds_bpermute_b32 v5, v138, v4
	s_waitcnt lgkmcnt(0)
	v_max_f32_e32 v5, v5, v5
	v_max_f32_e32 v4, v4, v5
	ds_bpermute_b32 v5, v139, v4
	s_waitcnt lgkmcnt(0)
	v_max_f32_e32 v5, v5, v5
	v_max_f32_e32 v4, v4, v5
	ds_bpermute_b32 v5, v140, v4
	s_waitcnt lgkmcnt(0)
	v_max_f32_e32 v5, v5, v5
	v_max_f32_e32 v4, v4, v5
	ds_bpermute_b32 v5, v141, v4
	s_waitcnt lgkmcnt(0)
	v_max3_f32 v4, v4, v5, s5
	s_and_saveexec_b64 s[24:25], s[40:41]
	s_cbranch_execz .LBB0_505
	s_add_u32 s6, s78, s0
	s_addc_u32 s7, s79, s4
	v_mul_f32_e32 v5, 0x38820610, v4
	global_store_dword v193, v5, s[6:7]
	s_branch .LBB0_505

; __device__ __forceinline__ float bflo(unsigned w) { return __uint_as_float(w << 16); }
; __device__ __forceinline__ float bfhi(unsigned w) { return __uint_as_float(w & 0xffff0000u); }
; __global__ void __launch_bounds__(NWAVES * 64, 2) mega_fwd(Args args) {
;     ...
;             const bf16* xr = XB + (size_t)row * DM; const bf16* mr = MP + (size_t)row * DM; float* yr = outg + (size_t)row * DM; f32x4 v[16]; float s = 0.f;
; #pragma unroll
;             for (int j = 0; j < 16; ++j) { const v2u xv = *(const v2u*)(xr + 4 * lane + 256 * j); const v2u m = *(const v2u*)(mr + 4 * lane + 256 * j);
;                 v[j] = (f32x4){bflo(xv[0]), bfhi(xv[0]), bflo(xv[1]), bfhi(xv[1])} * DEEP_ALPHA + (f32x4){bflo(m[0]), bfhi(m[0]), bflo(m[1]), bfhi(m[1])}; s += (v[j][0] + v[j][1]) + (v[j][2] + v[j][3]); }
;             const float mean = wave_sum(s, lane) * (1.0f / DM); float q = 0.f;
.LBB0_662:
	s_nop 1
	v_add_co_u32_e32 v82, vcc, 0xdffff000, v52
	s_brev_b32 s0, 7
	s_nop 0
	v_addc_co_u32_e32 v83, vcc, -1, v53, vcc
	v_add_co_u32_e32 v70, vcc, 0xfffff000, v52
	global_load_dwordx2 v[138:139], v[82:83], off offset:-3584
	s_nop 0
	v_addc_co_u32_e32 v71, vcc, -1, v53, vcc
	global_load_dwordx2 v[140:141], v[70:71], off offset:-3584
	v_add_co_u32_e32 v114, vcc, s0, v52
	s_nop 1
	v_addc_co_u32_e32 v115, vcc, -1, v53, vcc
	s_nop 0
	global_load_dwordx2 v[142:143], v[82:83], off offset:-3072
	global_load_dwordx2 v[144:145], v[70:71], off offset:-3072
	s_nop 0
	global_load_dwordx2 v[146:147], v[82:83], off offset:-2560
	global_load_dwordx2 v[148:149], v[70:71], off offset:-2560
	global_load_dwordx2 v[150:151], v[82:83], off offset:-2048
	global_load_dwordx2 v[152:153], v[70:71], off offset:-2048
	s_nop 0
	s_nop 0
	global_load_dwordx2 v[154:155], v[82:83], off offset:-1536
	global_load_dwordx2 v[156:157], v[70:71], off offset:-1536
	s_nop 0
	global_load_dwordx2 v[158:159], v[82:83], off offset:-1024
	global_load_dwordx2 v[160:161], v[70:71], off offset:-1024
	global_load_dwordx2 v[162:163], v[82:83], off offset:-512
	s_nop 0
	global_load_dwordx2 v[164:165], v[70:71], off offset:-512
	s_nop 0
	s_nop 0
	global_load_dwordx2 v[166:167], v[82:83], off
	s_nop 0
	global_load_dwordx2 v[168:169], v[52:53], off offset:-4096
	s_nop 0
	global_load_dwordx2 v[170:171], v[114:115], off offset:-3584
	global_load_dwordx2 v[172:173], v[52:53], off offset:-3584
	global_load_dwordx2 v[174:175], v[114:115], off offset:-3072
	global_load_dwordx2 v[176:177], v[52:53], off offset:-3072
	s_nop 0
	s_nop 0
	global_load_dwordx2 v[178:179], v[114:115], off offset:-2560
	global_load_dwordx2 v[180:181], v[52:53], off offset:-2560
	s_nop 0
	global_load_dwordx2 v[182:183], v[114:115], off offset:-2048
	global_load_dwordx2 v[184:185], v[52:53], off offset:-2048
	global_load_dwordx2 v[186:187], v[114:115], off offset:-1536
	global_load_dwordx2 v[188:189], v[52:53], off offset:-1536
	s_nop 0
	s_nop 0
	global_load_dwordx2 v[190:191], v[114:115], off offset:-1024
	global_load_dwordx2 v[194:195], v[52:53], off offset:-1024
	s_nop 0
	global_load_dwordx2 v[196:197], v[114:115], off offset:-512
	global_load_dwordx2 v[198:199], v[52:53], off offset:-512
	global_load_dwordx2 v[200:201], v[114:115], off
	s_nop 0
	global_load_dwordx2 v[202:203], v[52:53], off
	s_movk_i32 s0, 0x1000
	s_nop 1
	s_waitcnt vmcnt(31)
	v_lshlrev_b32_e32 v58, 16, v138
	v_and_b32_e32 v59, 0xffff0000, v138
	v_lshlrev_b32_e32 v54, 16, v139
	v_and_b32_e32 v55, 0xffff0000, v139
	s_waitcnt vmcnt(30)
	v_lshlrev_b32_e32 v60, 16, v140
	v_and_b32_e32 v61, 0xffff0000, v140
	v_lshlrev_b32_e32 v56, 16, v141
	v_and_b32_e32 v57, 0xffff0000, v141
	v_pk_fma_f32 v[54:55], v[54:55], s[88:89], v[56:57] op_sel_hi:[1,0,1]
	v_pk_fma_f32 v[56:57], v[58:59], s[88:89], v[60:61] op_sel_hi:[1,0,1]
	v_mov_b32_e32 v61, v55
	v_pk_mov_b32 v[58:59], v[56:57], v[54:55] op_sel:[1,0]
	v_mov_b32_e32 v60, v56
	v_pk_add_f32 v[58:59], v[58:59], v[60:61]
	s_nop 0
	v_add_f32_e32 v58, v58, v59
	v_add_f32_e32 v72, 0, v58
	s_nop 1
	s_waitcnt vmcnt(29)
	v_lshlrev_b32_e32 v62, 16, v142
	v_and_b32_e32 v63, 0xffff0000, v142
	v_lshlrev_b32_e32 v58, 16, v143
	v_and_b32_e32 v59, 0xffff0000, v143
	s_waitcnt vmcnt(28)
	v_lshlrev_b32_e32 v64, 16, v144
	v_and_b32_e32 v65, 0xffff0000, v144
	v_lshlrev_b32_e32 v60, 16, v145
	v_and_b32_e32 v61, 0xffff0000, v145
	v_pk_fma_f32 v[60:61], v[58:59], s[88:89], v[60:61] op_sel_hi:[1,0,1]
	v_pk_fma_f32 v[58:59], v[62:63], s[88:89], v[64:65] op_sel_hi:[1,0,1]
	v_mov_b32_e32 v65, v61
	v_pk_mov_b32 v[62:63], v[58:59], v[60:61] op_sel:[1,0]
	v_mov_b32_e32 v64, v58
	v_pk_add_f32 v[62:63], v[62:63], v[64:65]
	s_nop 0
	v_pk_add_f32 v[74:75], v[62:63], v[62:63] op_sel:[0,1] op_sel_hi:[1,0]
	s_nop 1
	s_waitcnt vmcnt(27)
	v_lshlrev_b32_e32 v66, 16, v146
	v_and_b32_e32 v67, 0xffff0000, v146
	v_lshlrev_b32_e32 v62, 16, v147
	v_and_b32_e32 v63, 0xffff0000, v147
	s_waitcnt vmcnt(26)
	v_lshlrev_b32_e32 v68, 16, v148
	v_and_b32_e32 v69, 0xffff0000, v148
	v_lshlrev_b32_e32 v64, 16, v149
	v_and_b32_e32 v65, 0xffff0000, v149
	v_pk_fma_f32 v[64:65], v[62:63], s[88:89], v[64:65] op_sel_hi:[1,0,1]
	v_pk_fma_f32 v[62:63], v[66:67], s[88:89], v[68:69] op_sel_hi:[1,0,1]
	s_nop 1
	v_add_f32_e32 v76, v62, v63
	v_add_f32_e32 v78, v64, v65
	s_waitcnt vmcnt(25)
	v_lshlrev_b32_e32 v80, 16, v150
	v_and_b32_e32 v81, 0xffff0000, v150
	v_lshlrev_b32_e32 v66, 16, v151
	v_and_b32_e32 v67, 0xffff0000, v151
	s_waitcnt vmcnt(24)
	v_lshlrev_b32_e32 v84, 16, v152
	v_and_b32_e32 v85, 0xffff0000, v152
	v_lshlrev_b32_e32 v68, 16, v153
	v_and_b32_e32 v69, 0xffff0000, v153
	v_pk_fma_f32 v[68:69], v[66:67], s[88:89], v[68:69] op_sel_hi:[1,0,1]
	v_pk_fma_f32 v[66:67], v[80:81], s[88:89], v[84:85] op_sel_hi:[1,0,1]
	v_mov_b32_e32 v77, v68
	v_mov_b32_e32 v73, v66
	v_mov_b32_e32 v75, v67
	v_mov_b32_e32 v79, v69
	v_pk_add_f32 v[72:73], v[72:73], v[74:75]
	v_pk_add_f32 v[74:75], v[76:77], v[78:79]
	s_nop 0
	v_pk_add_f32 v[72:73], v[72:73], v[74:75]
	s_nop 0
	v_pk_add_f32 v[84:85], v[72:73], v[72:73] op_sel:[0,1] op_sel_hi:[1,0]
	s_nop 1
	s_waitcnt vmcnt(23)
	v_lshlrev_b32_e32 v76, 16, v154
	v_and_b32_e32 v77, 0xffff0000, v154
	v_lshlrev_b32_e32 v72, 16, v155
	v_and_b32_e32 v73, 0xffff0000, v155
	s_waitcnt vmcnt(22)
	v_lshlrev_b32_e32 v78, 16, v156
	v_and_b32_e32 v79, 0xffff0000, v156
	v_lshlrev_b32_e32 v74, 16, v157
	v_and_b32_e32 v75, 0xffff0000, v157
	v_pk_fma_f32 v[80:81], v[72:73], s[88:89], v[74:75] op_sel_hi:[1,0,1]
	v_pk_fma_f32 v[78:79], v[76:77], s[88:89], v[78:79] op_sel_hi:[1,0,1]
	v_mov_b32_e32 v75, v81
	v_pk_mov_b32 v[72:73], v[78:79], v[80:81] op_sel:[1,0]
	v_mov_b32_e32 v74, v78
	v_pk_add_f32 v[72:73], v[72:73], v[74:75]
	s_nop 0
	v_pk_add_f32 v[86:87], v[72:73], v[72:73] op_sel:[0,1] op_sel_hi:[1,0]
	s_nop 1
	s_waitcnt vmcnt(21)
; __device__ __forceinline__ float bflo(unsigned w) { return __uint_as_float(w << 16); }
; __device__ __forceinline__ float bfhi(unsigned w) { return __uint_as_float(w & 0xffff0000u); }
; __global__ void __launch_bounds__(NWAVES * 64, 2) mega_fwd(Args args) {
;     ...
;             for (int j = 0; j < 16; ++j) { const v2u xv = *(const v2u*)(xr + 4 * lane + 256 * j); const v2u m = *(const v2u*)(mr + 4 * lane + 256 * j);
;                 v[j] = (f32x4){bflo(xv[0]), bfhi(xv[0]), bflo(xv[1]), bfhi(xv[1])} * DEEP_ALPHA + (f32x4){bflo(m[0]), bfhi(m[0]), bflo(m[1]), bfhi(m[1])}; s += (v[j][0] + v[j][1]) + (v[j][2] + v[j][3]); }
;             const float mean = wave_sum(s, lane) * (1.0f / DM); float q = 0.f;
	v_lshlrev_b32_e32 v88, 16, v158
	v_and_b32_e32 v89, 0xffff0000, v158
	v_lshlrev_b32_e32 v72, 16, v159
	v_and_b32_e32 v73, 0xffff0000, v159
	s_waitcnt vmcnt(20)
	v_lshlrev_b32_e32 v90, 16, v160
	v_and_b32_e32 v91, 0xffff0000, v160
	v_lshlrev_b32_e32 v74, 16, v161
	v_and_b32_e32 v75, 0xffff0000, v161
	v_pk_fma_f32 v[76:77], v[72:73], s[88:89], v[74:75] op_sel_hi:[1,0,1]
	s_nop 1
	v_pk_fma_f32 v[74:75], v[88:89], s[88:89], v[90:91] op_sel_hi:[1,0,1]
	v_add_f32_e32 v90, v76, v77
	v_add_f32_e32 v88, v74, v75
	s_waitcnt vmcnt(19)
	v_lshlrev_b32_e32 v92, 16, v162
	v_and_b32_e32 v93, 0xffff0000, v162
	v_lshlrev_b32_e32 v72, 16, v163
	v_and_b32_e32 v73, 0xffff0000, v163
	s_waitcnt vmcnt(18)
	v_lshlrev_b32_e32 v94, 16, v164
	v_and_b32_e32 v95, 0xffff0000, v164
	v_lshlrev_b32_e32 v70, 16, v165
	v_and_b32_e32 v71, 0xffff0000, v165
	v_pk_fma_f32 v[72:73], v[72:73], s[88:89], v[70:71] op_sel_hi:[1,0,1]
	v_pk_fma_f32 v[70:71], v[92:93], s[88:89], v[94:95] op_sel_hi:[1,0,1]
	v_mov_b32_e32 v89, v72
	v_mov_b32_e32 v85, v70
	v_mov_b32_e32 v87, v71
	v_mov_b32_e32 v91, v73
	v_pk_add_f32 v[84:85], v[84:85], v[86:87]
	v_pk_add_f32 v[86:87], v[88:89], v[90:91]
	s_nop 0
	v_pk_add_f32 v[84:85], v[84:85], v[86:87]
	s_nop 0
	v_pk_add_f32 v[94:95], v[84:85], v[84:85] op_sel:[0,1] op_sel_hi:[1,0]
	s_nop 1
	s_waitcnt vmcnt(17)
	v_lshlrev_b32_e32 v86, 16, v166
	v_and_b32_e32 v87, 0xffff0000, v166
	v_lshlrev_b32_e32 v82, 16, v167
	v_and_b32_e32 v83, 0xffff0000, v167
	s_waitcnt vmcnt(16)
	v_lshlrev_b32_e32 v88, 16, v168
	v_and_b32_e32 v89, 0xffff0000, v168
	v_lshlrev_b32_e32 v84, 16, v169
	v_and_b32_e32 v85, 0xffff0000, v169
	v_pk_fma_f32 v[84:85], v[82:83], s[88:89], v[84:85] op_sel_hi:[1,0,1]
	v_pk_fma_f32 v[82:83], v[86:87], s[88:89], v[88:89] op_sel_hi:[1,0,1]
	v_mov_b32_e32 v89, v85
	v_pk_mov_b32 v[86:87], v[82:83], v[84:85] op_sel:[1,0]
	v_mov_b32_e32 v88, v82
	v_pk_add_f32 v[86:87], v[86:87], v[88:89]
	s_nop 0
	v_pk_add_f32 v[96:97], v[86:87], v[86:87] op_sel:[0,1] op_sel_hi:[1,0]
	s_nop 1
	s_waitcnt vmcnt(15)
	v_lshlrev_b32_e32 v90, 16, v170
	v_and_b32_e32 v91, 0xffff0000, v170
	v_lshlrev_b32_e32 v86, 16, v171
	v_and_b32_e32 v87, 0xffff0000, v171
	s_waitcnt vmcnt(14)
	v_lshlrev_b32_e32 v92, 16, v172
	v_and_b32_e32 v93, 0xffff0000, v172
	v_lshlrev_b32_e32 v88, 16, v173
	v_and_b32_e32 v89, 0xffff0000, v173
	v_pk_fma_f32 v[88:89], v[86:87], s[88:89], v[88:89] op_sel_hi:[1,0,1]
	v_pk_fma_f32 v[86:87], v[90:91], s[88:89], v[92:93] op_sel_hi:[1,0,1]
	s_nop 1
	v_add_f32_e32 v98, v86, v87
	v_add_f32_e32 v100, v88, v89
	s_waitcnt vmcnt(13)
	v_lshlrev_b32_e32 v102, 16, v174
	v_and_b32_e32 v103, 0xffff0000, v174
	v_lshlrev_b32_e32 v90, 16, v175
	v_and_b32_e32 v91, 0xffff0000, v175
	s_waitcnt vmcnt(12)
	v_lshlrev_b32_e32 v104, 16, v176
	v_and_b32_e32 v105, 0xffff0000, v176
	v_lshlrev_b32_e32 v92, 16, v177
	v_and_b32_e32 v93, 0xffff0000, v177
	v_pk_fma_f32 v[92:93], v[90:91], s[88:89], v[92:93] op_sel_hi:[1,0,1]
	v_pk_fma_f32 v[90:91], v[102:103], s[88:89], v[104:105] op_sel_hi:[1,0,1]
	v_mov_b32_e32 v99, v92
	v_mov_b32_e32 v95, v90
	v_mov_b32_e32 v97, v91
	v_mov_b32_e32 v101, v93
	v_pk_add_f32 v[94:95], v[94:95], v[96:97]
	v_pk_add_f32 v[96:97], v[98:99], v[100:101]
	s_nop 0
	v_pk_add_f32 v[94:95], v[94:95], v[96:97]
	s_nop 0
	v_pk_add_f32 v[106:107], v[94:95], v[94:95] op_sel:[0,1] op_sel_hi:[1,0]
	s_nop 1
	s_waitcnt vmcnt(11)
	v_lshlrev_b32_e32 v98, 16, v178
	v_and_b32_e32 v99, 0xffff0000, v178
	v_lshlrev_b32_e32 v94, 16, v179
	v_and_b32_e32 v95, 0xffff0000, v179
	s_waitcnt vmcnt(10)
	v_lshlrev_b32_e32 v100, 16, v180
	v_and_b32_e32 v101, 0xffff0000, v180
	v_lshlrev_b32_e32 v96, 16, v181
	v_and_b32_e32 v97, 0xffff0000, v181
	v_pk_fma_f32 v[96:97], v[94:95], s[88:89], v[96:97] op_sel_hi:[1,0,1]
	v_pk_fma_f32 v[94:95], v[98:99], s[88:89], v[100:101] op_sel_hi:[1,0,1]
	v_mov_b32_e32 v101, v97
	v_pk_mov_b32 v[98:99], v[94:95], v[96:97] op_sel:[1,0]
	v_mov_b32_e32 v100, v94
	v_pk_add_f32 v[98:99], v[98:99], v[100:101]
	s_nop 0
	v_pk_add_f32 v[108:109], v[98:99], v[98:99] op_sel:[0,1] op_sel_hi:[1,0]
	s_nop 1
	s_waitcnt vmcnt(9)
	v_lshlrev_b32_e32 v102, 16, v182
	v_and_b32_e32 v103, 0xffff0000, v182
	v_lshlrev_b32_e32 v98, 16, v183
	v_and_b32_e32 v99, 0xffff0000, v183
	s_waitcnt vmcnt(8)
	v_lshlrev_b32_e32 v104, 16, v184
	v_and_b32_e32 v105, 0xffff0000, v184
	v_lshlrev_b32_e32 v100, 16, v185
	v_and_b32_e32 v101, 0xffff0000, v185
	v_pk_fma_f32 v[100:101], v[98:99], s[88:89], v[100:101] op_sel_hi:[1,0,1]
	v_pk_fma_f32 v[98:99], v[102:103], s[88:89], v[104:105] op_sel_hi:[1,0,1]
	s_nop 1
	v_add_f32_e32 v110, v98, v99
	v_add_f32_e32 v112, v100, v101
	s_waitcnt vmcnt(7)
	v_lshlrev_b32_e32 v116, 16, v186
	v_and_b32_e32 v117, 0xffff0000, v186
	v_lshlrev_b32_e32 v102, 16, v187
	v_and_b32_e32 v103, 0xffff0000, v187
	s_waitcnt vmcnt(6)
	v_lshlrev_b32_e32 v118, 16, v188
	v_and_b32_e32 v119, 0xffff0000, v188
	v_lshlrev_b32_e32 v104, 16, v189
	v_and_b32_e32 v105, 0xffff0000, v189
	v_pk_fma_f32 v[104:105], v[102:103], s[88:89], v[104:105] op_sel_hi:[1,0,1]
	v_pk_fma_f32 v[102:103], v[116:117], s[88:89], v[118:119] op_sel_hi:[1,0,1]
	v_mov_b32_e32 v111, v104
	v_mov_b32_e32 v107, v102
	v_mov_b32_e32 v109, v103
	v_mov_b32_e32 v113, v105
	v_pk_add_f32 v[106:107], v[106:107], v[108:109]
	v_pk_add_f32 v[108:109], v[110:111], v[112:113]
	s_nop 0
	v_pk_add_f32 v[106:107], v[106:107], v[108:109]
	s_nop 0
	v_pk_add_f32 v[118:119], v[106:107], v[106:107] op_sel:[0,1] op_sel_hi:[1,0]
	s_nop 1
	s_waitcnt vmcnt(5)
	v_lshlrev_b32_e32 v110, 16, v190
	v_and_b32_e32 v111, 0xffff0000, v190
	v_lshlrev_b32_e32 v106, 16, v191
	v_and_b32_e32 v107, 0xffff0000, v191
	s_waitcnt vmcnt(4)
; __device__ __forceinline__ float bflo(unsigned w) { return __uint_as_float(w << 16); }
; __device__ __forceinline__ float bfhi(unsigned w) { return __uint_as_float(w & 0xffff0000u); }
; __global__ void __launch_bounds__(NWAVES * 64, 2) mega_fwd(Args args) {
;     ...
;                 v[j] = (f32x4){bflo(xv[0]), bfhi(xv[0]), bflo(xv[1]), bfhi(xv[1])} * DEEP_ALPHA + (f32x4){bflo(m[0]), bfhi(m[0]), bflo(m[1]), bfhi(m[1])}; s += (v[j][0] + v[j][1]) + (v[j][2] + v[j][3]); }
;             const float mean = wave_sum(s, lane) * (1.0f / DM); float q = 0.f;
; #pragma unroll
;             for (int j = 0; j < 16; ++j) { v[j] = v[j] - mean; q += (v[j][0] * v[j][0] + v[j][1] * v[j][1]) + (v[j][2] * v[j][2] + v[j][3] * v[j][3]); }
	v_lshlrev_b32_e32 v112, 16, v194
	v_and_b32_e32 v113, 0xffff0000, v194
	v_lshlrev_b32_e32 v108, 16, v195
	v_and_b32_e32 v109, 0xffff0000, v195
	v_pk_fma_f32 v[108:109], v[106:107], s[88:89], v[108:109] op_sel_hi:[1,0,1]
	v_pk_fma_f32 v[106:107], v[110:111], s[88:89], v[112:113] op_sel_hi:[1,0,1]
	v_mov_b32_e32 v113, v109
	v_pk_mov_b32 v[110:111], v[106:107], v[108:109] op_sel:[1,0]
	v_mov_b32_e32 v112, v106
	v_pk_add_f32 v[110:111], v[110:111], v[112:113]
	s_nop 0
	v_pk_add_f32 v[120:121], v[110:111], v[110:111] op_sel:[0,1] op_sel_hi:[1,0]
	s_nop 1
	s_waitcnt vmcnt(3)
	v_lshlrev_b32_e32 v116, 16, v196
	v_and_b32_e32 v117, 0xffff0000, v196
	v_lshlrev_b32_e32 v110, 16, v197
	v_and_b32_e32 v111, 0xffff0000, v197
	s_waitcnt vmcnt(2)
	v_lshlrev_b32_e32 v122, 16, v198
	v_and_b32_e32 v123, 0xffff0000, v198
	v_lshlrev_b32_e32 v112, 16, v199
	v_and_b32_e32 v113, 0xffff0000, v199
	v_pk_fma_f32 v[112:113], v[110:111], s[88:89], v[112:113] op_sel_hi:[1,0,1]
	v_pk_fma_f32 v[110:111], v[116:117], s[88:89], v[122:123] op_sel_hi:[1,0,1]
	s_nop 1
	v_add_f32_e32 v122, v110, v111
	v_add_f32_e32 v124, v112, v113
	s_waitcnt vmcnt(1)
	v_lshlrev_b32_e32 v132, 16, v200
	v_and_b32_e32 v133, 0xffff0000, v200
	v_lshlrev_b32_e32 v114, 16, v201
	v_and_b32_e32 v115, 0xffff0000, v201
	s_waitcnt vmcnt(0)
	v_lshlrev_b32_e32 v134, 16, v202
	v_and_b32_e32 v135, 0xffff0000, v202
	v_lshlrev_b32_e32 v116, 16, v203
	v_and_b32_e32 v117, 0xffff0000, v203
	v_pk_fma_f32 v[114:115], v[114:115], s[88:89], v[116:117] op_sel_hi:[1,0,1]
	v_pk_fma_f32 v[116:117], v[132:133], s[88:89], v[134:135] op_sel_hi:[1,0,1]
	v_mov_b32_e32 v123, v114
	v_mov_b32_e32 v119, v116
	v_mov_b32_e32 v121, v117
	v_mov_b32_e32 v125, v115
	v_pk_add_f32 v[118:119], v[118:119], v[120:121]
	v_pk_add_f32 v[120:121], v[122:123], v[124:125]
	s_nop 0
	v_pk_add_f32 v[118:119], v[118:119], v[120:121]
	s_nop 0
	v_add_f32_e32 v118, v118, v119
	ds_bpermute_b32 v119, v126, v118
	s_waitcnt lgkmcnt(0)
	v_add_f32_e32 v118, v118, v119
	ds_bpermute_b32 v119, v127, v118
	s_waitcnt lgkmcnt(0)
	v_add_f32_e32 v118, v118, v119
	ds_bpermute_b32 v119, v128, v118
	s_waitcnt lgkmcnt(0)
	v_add_f32_e32 v118, v118, v119
	ds_bpermute_b32 v119, v129, v118
	s_waitcnt lgkmcnt(0)
	v_add_f32_e32 v118, v118, v119
	ds_bpermute_b32 v119, v130, v118
	s_waitcnt lgkmcnt(0)
	v_add_f32_e32 v118, v118, v119
	ds_bpermute_b32 v119, v131, v118
	s_waitcnt lgkmcnt(0)
	v_add_f32_e32 v132, v118, v119
	v_fmamk_f32 v57, v132, 0xb9800000, v57
	v_fmac_f32_e32 v56, 0xb9800000, v132
	v_fmamk_f32 v55, v132, 0xb9800000, v55
	v_fmac_f32_e32 v54, 0xb9800000, v132
	v_pk_mul_f32 v[118:119], v[54:55], v[54:55]
	v_pk_mul_f32 v[120:121], v[56:57], v[56:57]
	v_fmamk_f32 v59, v132, 0xb9800000, v59
	v_pk_mov_b32 v[122:123], v[120:121], v[118:119] op_sel:[1,0]
	v_mov_b32_e32 v121, v119
	v_fmac_f32_e32 v58, 0xb9800000, v132
	v_fmamk_f32 v61, v132, 0xb9800000, v61
	v_fmac_f32_e32 v60, 0xb9800000, v132
	v_pk_add_f32 v[118:119], v[122:123], v[120:121]
	v_pk_mul_f32 v[120:121], v[60:61], v[60:61]
	v_pk_mul_f32 v[122:123], v[58:59], v[58:59]
	v_fmamk_f32 v67, v132, 0xb9800000, v67
	v_pk_mov_b32 v[124:125], v[122:123], v[120:121] op_sel:[1,0]
	v_mov_b32_e32 v123, v121
	v_pk_add_f32 v[120:121], v[124:125], v[122:123]
	v_fmac_f32_e32 v66, 0xb9800000, v132
	v_mul_f32_e32 v122, v66, v66
	v_mul_f32_e32 v123, v67, v67
	v_pk_add_f32 v[118:119], v[118:119], v[118:119] op_sel:[0,1] op_sel_hi:[1,0]
	v_pk_add_f32 v[120:121], v[120:121], v[120:121] op_sel:[0,1] op_sel_hi:[1,0]
	v_fmamk_f32 v63, v132, 0xb9800000, v63
	v_fmamk_f32 v65, v132, 0xb9800000, v65
	v_mov_b32_e32 v119, v122
	v_mov_b32_e32 v121, v123
	v_fmac_f32_e32 v62, 0xb9800000, v132
	v_fmac_f32_e32 v64, 0xb9800000, v132
	v_fmamk_f32 v69, v132, 0xb9800000, v69
	v_fmac_f32_e32 v68, 0xb9800000, v132
	v_pk_add_f32 v[118:119], v[118:119], v[120:121]
	v_mul_f32_e32 v120, v63, v63
	v_mul_f32_e32 v122, v65, v65
	v_mul_f32_e32 v124, v68, v68
	v_mul_f32_e32 v125, v69, v69
	v_pk_fma_f32 v[120:121], v[62:63], v[62:63], v[120:121] op_sel_hi:[1,1,0]
	v_pk_fma_f32 v[122:123], v[64:65], v[64:65], v[122:123] op_sel_hi:[1,1,0]
	v_mov_b32_e32 v121, v124
	v_mov_b32_e32 v123, v125
	v_pk_add_f32 v[120:121], v[120:121], v[122:123]
	v_fmamk_f32 v79, v132, 0xb9800000, v79
	v_fmac_f32_e32 v78, 0xb9800000, v132
	v_fmamk_f32 v81, v132, 0xb9800000, v81
	v_fmac_f32_e32 v80, 0xb9800000, v132
	v_pk_add_f32 v[118:119], v[118:119], v[120:121]
	v_pk_mul_f32 v[120:121], v[80:81], v[80:81]
	v_pk_mul_f32 v[122:123], v[78:79], v[78:79]
	v_fmamk_f32 v71, v132, 0xb9800000, v71
	v_pk_mov_b32 v[124:125], v[122:123], v[120:121] op_sel:[1,0]
	v_mov_b32_e32 v123, v121
	v_pk_add_f32 v[120:121], v[124:125], v[122:123]
	v_fmac_f32_e32 v70, 0xb9800000, v132
	v_mul_f32_e32 v122, v70, v70
	v_mul_f32_e32 v123, v71, v71
	v_pk_add_f32 v[118:119], v[118:119], v[118:119] op_sel:[0,1] op_sel_hi:[1,0]
	v_pk_add_f32 v[120:121], v[120:121], v[120:121] op_sel:[0,1] op_sel_hi:[1,0]
	v_fmamk_f32 v75, v132, 0xb9800000, v75
	v_fmamk_f32 v77, v132, 0xb9800000, v77
	v_mov_b32_e32 v119, v122
	v_mov_b32_e32 v121, v123
	v_fmac_f32_e32 v74, 0xb9800000, v132
	v_fmac_f32_e32 v76, 0xb9800000, v132
	v_fmamk_f32 v73, v132, 0xb9800000, v73
	v_fmac_f32_e32 v72, 0xb9800000, v132
	v_pk_add_f32 v[118:119], v[118:119], v[120:121]
	v_mul_f32_e32 v120, v75, v75
	v_mul_f32_e32 v122, v77, v77
	v_mul_f32_e32 v124, v72, v72
	v_mul_f32_e32 v125, v73, v73
	v_pk_fma_f32 v[120:121], v[74:75], v[74:75], v[120:121] op_sel_hi:[1,1,0]
	v_pk_fma_f32 v[122:123], v[76:77], v[76:77], v[122:123] op_sel_hi:[1,1,0]
	v_mov_b32_e32 v121, v124
	v_mov_b32_e32 v123, v125
	v_pk_add_f32 v[120:121], v[120:121], v[122:123]
; __global__ void __launch_bounds__(NWAVES * 64, 2) mega_fwd(Args args) {
;     ...
; #pragma unroll
;             for (int j = 0; j < 16; ++j) { v[j] = v[j] - mean; q += (v[j][0] * v[j][0] + v[j][1] * v[j][1]) + (v[j][2] * v[j][2] + v[j][3] * v[j][3]); }
;             const float rstd = 1.0f / sqrtf(wave_sum(q, lane) * (1.0f / DM) + LN_EPS);
	v_fmamk_f32 v83, v132, 0xb9800000, v83
	v_fmac_f32_e32 v82, 0xb9800000, v132
	v_fmamk_f32 v85, v132, 0xb9800000, v85
	v_fmac_f32_e32 v84, 0xb9800000, v132
	v_pk_add_f32 v[118:119], v[118:119], v[120:121]
	v_pk_mul_f32 v[120:121], v[84:85], v[84:85]
	v_pk_mul_f32 v[122:123], v[82:83], v[82:83]
	v_fmamk_f32 v91, v132, 0xb9800000, v91
	v_pk_mov_b32 v[124:125], v[122:123], v[120:121] op_sel:[1,0]
	v_mov_b32_e32 v123, v121
	v_pk_add_f32 v[120:121], v[124:125], v[122:123]
	v_fmac_f32_e32 v90, 0xb9800000, v132
	v_mul_f32_e32 v122, v90, v90
	v_mul_f32_e32 v123, v91, v91
	v_pk_add_f32 v[118:119], v[118:119], v[118:119] op_sel:[0,1] op_sel_hi:[1,0]
	v_pk_add_f32 v[120:121], v[120:121], v[120:121] op_sel:[0,1] op_sel_hi:[1,0]
	v_fmamk_f32 v87, v132, 0xb9800000, v87
	v_fmamk_f32 v89, v132, 0xb9800000, v89
	v_mov_b32_e32 v119, v122
	v_mov_b32_e32 v121, v123
	v_fmac_f32_e32 v86, 0xb9800000, v132
	v_fmac_f32_e32 v88, 0xb9800000, v132
	v_fmamk_f32 v93, v132, 0xb9800000, v93
	v_fmac_f32_e32 v92, 0xb9800000, v132
	v_pk_add_f32 v[118:119], v[118:119], v[120:121]
	v_mul_f32_e32 v120, v87, v87
	v_mul_f32_e32 v122, v89, v89
	v_mul_f32_e32 v124, v92, v92
	v_mul_f32_e32 v125, v93, v93
	v_pk_fma_f32 v[120:121], v[86:87], v[86:87], v[120:121] op_sel_hi:[1,1,0]
	v_pk_fma_f32 v[122:123], v[88:89], v[88:89], v[122:123] op_sel_hi:[1,1,0]
	v_mov_b32_e32 v121, v124
	v_mov_b32_e32 v123, v125
	v_pk_add_f32 v[120:121], v[120:121], v[122:123]
	v_fmamk_f32 v95, v132, 0xb9800000, v95
	v_fmac_f32_e32 v94, 0xb9800000, v132
	v_fmamk_f32 v97, v132, 0xb9800000, v97
	v_fmac_f32_e32 v96, 0xb9800000, v132
	v_pk_add_f32 v[118:119], v[118:119], v[120:121]
	v_pk_mul_f32 v[120:121], v[96:97], v[96:97]
	v_pk_mul_f32 v[122:123], v[94:95], v[94:95]
	v_fmamk_f32 v103, v132, 0xb9800000, v103
	v_pk_mov_b32 v[124:125], v[122:123], v[120:121] op_sel:[1,0]
	v_mov_b32_e32 v123, v121
	v_pk_add_f32 v[120:121], v[124:125], v[122:123]
	v_fmac_f32_e32 v102, 0xb9800000, v132
	v_mul_f32_e32 v122, v102, v102
	v_mul_f32_e32 v123, v103, v103
	v_pk_add_f32 v[118:119], v[118:119], v[118:119] op_sel:[0,1] op_sel_hi:[1,0]
	v_pk_add_f32 v[120:121], v[120:121], v[120:121] op_sel:[0,1] op_sel_hi:[1,0]
	v_fmamk_f32 v99, v132, 0xb9800000, v99
	v_fmamk_f32 v101, v132, 0xb9800000, v101
	v_mov_b32_e32 v119, v122
	v_mov_b32_e32 v121, v123
	v_fmac_f32_e32 v98, 0xb9800000, v132
	v_fmac_f32_e32 v100, 0xb9800000, v132
	v_fmamk_f32 v105, v132, 0xb9800000, v105
	v_fmac_f32_e32 v104, 0xb9800000, v132
	v_pk_add_f32 v[118:119], v[118:119], v[120:121]
	v_mul_f32_e32 v120, v99, v99
	v_mul_f32_e32 v122, v101, v101
	v_mul_f32_e32 v124, v104, v104
	v_mul_f32_e32 v125, v105, v105
	v_pk_fma_f32 v[120:121], v[98:99], v[98:99], v[120:121] op_sel_hi:[1,1,0]
	v_pk_fma_f32 v[122:123], v[100:101], v[100:101], v[122:123] op_sel_hi:[1,1,0]
	v_mov_b32_e32 v121, v124
	v_mov_b32_e32 v123, v125
	v_pk_add_f32 v[120:121], v[120:121], v[122:123]
	v_fmamk_f32 v107, v132, 0xb9800000, v107
	v_fmac_f32_e32 v106, 0xb9800000, v132
	v_fmamk_f32 v109, v132, 0xb9800000, v109
	v_fmac_f32_e32 v108, 0xb9800000, v132
	v_pk_add_f32 v[118:119], v[118:119], v[120:121]
	v_pk_mul_f32 v[120:121], v[108:109], v[108:109]
	v_pk_mul_f32 v[122:123], v[106:107], v[106:107]
	v_fmamk_f32 v117, v132, 0xb9800000, v117
	v_pk_mov_b32 v[124:125], v[122:123], v[120:121] op_sel:[1,0]
	v_mov_b32_e32 v123, v121
	v_pk_add_f32 v[120:121], v[124:125], v[122:123]
	v_fmac_f32_e32 v116, 0xb9800000, v132
	v_mul_f32_e32 v122, v116, v116
	v_mul_f32_e32 v123, v117, v117
	v_pk_add_f32 v[118:119], v[118:119], v[118:119] op_sel:[0,1] op_sel_hi:[1,0]
	v_pk_add_f32 v[120:121], v[120:121], v[120:121] op_sel:[0,1] op_sel_hi:[1,0]
	v_fmamk_f32 v111, v132, 0xb9800000, v111
	v_fmamk_f32 v113, v132, 0xb9800000, v113
	v_mov_b32_e32 v119, v122
	v_mov_b32_e32 v121, v123
	v_fmac_f32_e32 v110, 0xb9800000, v132
	v_fmac_f32_e32 v112, 0xb9800000, v132
	v_fmamk_f32 v115, v132, 0xb9800000, v115
	v_fmac_f32_e32 v114, 0xb9800000, v132
	v_pk_add_f32 v[118:119], v[118:119], v[120:121]
	v_mul_f32_e32 v120, v111, v111
	v_mul_f32_e32 v122, v113, v113
	v_mul_f32_e32 v124, v114, v114
	v_mul_f32_e32 v125, v115, v115
	v_pk_fma_f32 v[120:121], v[110:111], v[110:111], v[120:121] op_sel_hi:[1,1,0]
	v_pk_fma_f32 v[122:123], v[112:113], v[112:113], v[122:123] op_sel_hi:[1,1,0]
	v_mov_b32_e32 v121, v124
	v_mov_b32_e32 v123, v125
	v_pk_add_f32 v[120:121], v[120:121], v[122:123]
	s_nop 0
	v_pk_add_f32 v[118:119], v[118:119], v[120:121]
	s_nop 0
	v_add_f32_e32 v118, v118, v119
	ds_bpermute_b32 v119, v126, v118
	s_waitcnt lgkmcnt(0)
	v_add_f32_e32 v118, v118, v119
	ds_bpermute_b32 v119, v127, v118
	s_waitcnt lgkmcnt(0)
	v_add_f32_e32 v118, v118, v119
	ds_bpermute_b32 v119, v128, v118
	s_waitcnt lgkmcnt(0)
	v_add_f32_e32 v118, v118, v119
	ds_bpermute_b32 v119, v129, v118
	s_waitcnt lgkmcnt(0)
	v_add_f32_e32 v118, v118, v119
	ds_bpermute_b32 v119, v130, v118
	s_waitcnt lgkmcnt(0)
	v_add_f32_e32 v118, v118, v119
	ds_bpermute_b32 v119, v131, v118
	s_waitcnt lgkmcnt(0)
; __global__ void __launch_bounds__(NWAVES * 64, 2) mega_fwd(Args args) {
;     ...
;             const float rstd = 1.0f / sqrtf(wave_sum(q, lane) * (1.0f / DM) + LN_EPS);
; #pragma unroll
;             for (int j = 0; j < 16; ++j) { const f32x4 gg = *(const f32x4*)(ln2_g + 4 * lane + 256 * j), bb = *(const f32x4*)(ln2_b + 4 * lane + 256 * j);
;                 *(f32x4*)(yr + 4 * lane + 256 * j) = v[j] * rstd * gg + bb; }
	v_add_f32_e32 v118, v118, v119
	v_mov_b32_e32 v119, 0x3727c5ac
	v_fmamk_f32 v118, v118, 0x39800000, v119
	v_cmp_gt_f32_e32 vcc, s55, v118
	v_mul_f32_e32 v119, 0x4f800000, v118
	s_nop 0
	v_cndmask_b32_e32 v118, v118, v119, vcc
	v_sqrt_f32_e32 v119, v118
	s_nop 0
	v_add_u32_e32 v120, -1, v119
	v_fma_f32 v121, -v120, v119, v118
	v_cmp_ge_f32_e64 s[38:39], 0, v121
	v_add_u32_e32 v121, 1, v119
	s_nop 0
	v_cndmask_b32_e64 v120, v119, v120, s[38:39]
	v_fma_f32 v119, -v121, v119, v118
	v_cmp_lt_f32_e64 s[38:39], 0, v119
	s_nop 1
	v_cndmask_b32_e64 v119, v120, v121, s[38:39]
	v_mul_f32_e32 v120, 0x37800000, v119
	v_cndmask_b32_e32 v119, v119, v120, vcc
	v_cmp_class_f32_e32 vcc, v118, v216
	s_nop 1
	v_cndmask_b32_e32 v118, v119, v118, vcc
	v_div_scale_f32 v119, s[4:5], v118, v118, 1.0
	v_rcp_f32_e32 v120, v119
	v_readlane_b32 s4, v255, 30
	v_readlane_b32 s5, v255, 31
	v_fma_f32 v121, -v119, v120, 1.0
	v_fmac_f32_e32 v120, v121, v120
	v_div_scale_f32 v121, vcc, 1.0, v118, 1.0
	v_mul_f32_e32 v122, v121, v120
	v_fma_f32 v123, -v119, v122, v121
	v_fmac_f32_e32 v122, v123, v120
	v_fma_f32 v119, -v119, v122, v121
	v_div_fmas_f32 v119, v119, v120, v122
	s_nop 1
	global_load_dwordx4 v[138:141], v[0:1], off
	global_load_dwordx4 v[142:145], v[2:3], off
	global_load_dwordx4 v[146:149], v[0:1], off offset:1024
	s_nop 0
	global_load_dwordx4 v[150:153], v[2:3], off offset:1024
	global_load_dwordx4 v[154:157], v[0:1], off offset:2048
	s_nop 0
	global_load_dwordx4 v[158:161], v[2:3], off offset:2048
	global_load_dwordx4 v[162:165], v[0:1], off offset:3072
	s_nop 0
	global_load_dwordx4 v[166:169], v[2:3], off offset:3072
	global_load_dwordx4 v[170:173], v[4:5], off
	s_nop 0
	global_load_dwordx4 v[174:177], v[6:7], off
	s_nop 0
	s_nop 0
	global_load_dwordx4 v[178:181], v[8:9], off
	s_nop 0
	global_load_dwordx4 v[182:185], v[10:11], off
	global_load_dwordx4 v[186:189], v[12:13], off
	s_nop 0
	global_load_dwordx4 v[194:197], v[14:15], off
	global_load_dwordx4 v[198:201], v[16:17], off
	s_nop 0
	global_load_dwordx4 v[202:205], v[18:19], off
	v_div_fixup_f32 v118, v119, v118, 1.0
	v_pk_mul_f32 v[136:137], v[118:119], v[56:57] op_sel_hi:[0,1]
	v_pk_mul_f32 v[54:55], v[118:119], v[54:55] op_sel_hi:[0,1]
	v_lshl_add_u64 v[120:121], s[42:43], 0, v[192:193]
	v_pk_mul_f32 v[60:61], v[118:119], v[60:61] op_sel_hi:[0,1]
	v_pk_mul_f32 v[58:59], v[118:119], v[58:59] op_sel_hi:[0,1]
	v_pk_mul_f32 v[64:65], v[118:119], v[64:65] op_sel_hi:[0,1]
	v_pk_mul_f32 v[62:63], v[118:119], v[62:63] op_sel_hi:[0,1]
	s_waitcnt vmcnt(14)
	v_pk_fma_f32 v[56:57], v[140:141], v[54:55], v[144:145]
	v_pk_fma_f32 v[54:55], v[138:139], v[136:137], v[142:143]
	global_store_dwordx4 v[120:121], v[54:57], off
	s_nop 0
	s_waitcnt vmcnt(12)
	v_pk_fma_f32 v[54:55], v[146:147], v[58:59], v[150:151]
	v_pk_fma_f32 v[56:57], v[148:149], v[60:61], v[152:153]
	global_store_dwordx4 v[120:121], v[54:57], off offset:1024
	s_nop 0
	s_waitcnt vmcnt(10)
	v_pk_fma_f32 v[54:55], v[154:155], v[62:63], v[158:159]
	v_pk_fma_f32 v[56:57], v[156:157], v[64:65], v[160:161]
	global_store_dwordx4 v[120:121], v[54:57], off offset:2048
	s_nop 0
	v_pk_mul_f32 v[62:63], v[118:119], v[68:69] op_sel_hi:[0,1]
	v_pk_mul_f32 v[64:65], v[118:119], v[66:67] op_sel_hi:[0,1]
	v_pk_mul_f32 v[66:67], v[118:119], v[76:77] op_sel_hi:[0,1]
	v_pk_mul_f32 v[68:69], v[118:119], v[74:75] op_sel_hi:[0,1]
	s_waitcnt vmcnt(8)
	v_pk_fma_f32 v[54:55], v[162:163], v[64:65], v[166:167]
	v_pk_fma_f32 v[56:57], v[164:165], v[62:63], v[168:169]
	global_store_dwordx4 v[120:121], v[54:57], off offset:3072
	s_nop 0
	v_pk_mul_f32 v[62:63], v[118:119], v[80:81] op_sel_hi:[0,1]
	v_pk_mul_f32 v[64:65], v[118:119], v[78:79] op_sel_hi:[0,1]
	s_waitcnt vmcnt(6)
	v_pk_fma_f32 v[56:57], v[172:173], v[62:63], v[176:177]
	v_add_co_u32_e32 v62, vcc, s0, v120
	v_pk_fma_f32 v[54:55], v[170:171], v[64:65], v[174:175]
	s_nop 0
	v_addc_co_u32_e32 v63, vcc, 0, v121, vcc
	v_add_co_u32_e32 v64, vcc, s15, v120
	s_movk_i32 s0, 0x3000
	s_nop 0
	v_addc_co_u32_e32 v65, vcc, 0, v121, vcc
	global_store_dwordx4 v[64:65], v[54:57], off offset:-4096
	s_nop 0
	s_waitcnt vmcnt(4)
	v_pk_fma_f32 v[54:55], v[178:179], v[68:69], v[182:183]
	v_pk_fma_f32 v[56:57], v[180:181], v[66:67], v[184:185]
	global_store_dwordx4 v[62:63], v[54:57], off offset:1024
	s_nop 0
	v_pk_mul_f32 v[66:67], v[118:119], v[72:73] op_sel_hi:[0,1]
	v_pk_mul_f32 v[68:69], v[118:119], v[70:71] op_sel_hi:[0,1]
	s_waitcnt vmcnt(2)
	v_pk_fma_f32 v[54:55], v[186:187], v[68:69], v[194:195]
	v_pk_fma_f32 v[56:57], v[188:189], v[66:67], v[196:197]
	global_store_dwordx4 v[62:63], v[54:57], off offset:2048
	s_nop 0
	v_pk_mul_f32 v[66:67], v[118:119], v[84:85] op_sel_hi:[0,1]
	v_pk_mul_f32 v[68:69], v[118:119], v[82:83] op_sel_hi:[0,1]
	s_waitcnt vmcnt(0)
	v_pk_fma_f32 v[54:55], v[198:199], v[68:69], v[202:203]
	v_pk_fma_f32 v[56:57], v[200:201], v[66:67], v[204:205]
	global_store_dwordx4 v[62:63], v[54:57], off offset:3072
	s_nop 1
	global_load_dwordx4 v[138:141], v[20:21], off
	s_nop 0
	global_load_dwordx4 v[142:145], v[22:23], off
	global_load_dwordx4 v[146:149], v[24:25], off
	s_nop 0
	global_load_dwordx4 v[150:153], v[26:27], off
	global_load_dwordx4 v[154:157], v[28:29], off
	s_nop 0
	global_load_dwordx4 v[158:161], v[30:31], off
	global_load_dwordx4 v[162:165], v[32:33], off
	s_nop 0
	global_load_dwordx4 v[166:169], v[34:35], off
	global_load_dwordx4 v[170:173], v[36:37], off
	s_nop 0
	global_load_dwordx4 v[174:177], v[38:39], off
	s_nop 0
	global_load_dwordx4 v[178:181], v[40:41], off
	s_nop 0
	global_load_dwordx4 v[182:185], v[42:43], off
	global_load_dwordx4 v[186:189], v[44:45], off
	s_nop 0
	global_load_dwordx4 v[194:197], v[46:47], off
	global_load_dwordx4 v[198:201], v[48:49], off
	s_nop 0
	global_load_dwordx4 v[202:205], v[50:51], off
	v_pk_mul_f32 v[62:63], v[118:119], v[88:89] op_sel_hi:[0,1]
	v_pk_mul_f32 v[66:67], v[118:119], v[86:87] op_sel_hi:[0,1]
	s_waitcnt vmcnt(14)
; __device__ __forceinline__ unsigned pk2(float lo, float hi) { return f2bf(lo) | (f2bf(hi) << 16); }
; __global__ void __launch_bounds__(NWAVES * 64, 2) mega_fwd(Args args) {
;     ...
;             for (int j = 0; j < 16; ++j) { const f32x4 gg = *(const f32x4*)(ln2_g + 4 * lane + 256 * j), bb = *(const f32x4*)(ln2_b + 4 * lane + 256 * j);
;                 *(f32x4*)(yr + 4 * lane + 256 * j) = v[j] * rstd * gg + bb; }
;             if (g == 0) {
;                 const float* xs = args.in[1] + (size_t)row * DM;
; #pragma unroll
;                 for (int jb = 0; jb < 4; ++jb) { f32x4 t[4];
; #pragma unroll
;                     for (int j = 0; j < 4; ++j) t[j] = *(const f32x4*)(xs + 4 * lane + 256 * (4 * jb + j));
; #pragma unroll
;                     for (int j = 0; j < 4; ++j) { v2u w; w.x = pk2(t[j][0], t[j][1]); w.y = pk2(t[j][2], t[j][3]); *(v2u*)(XB + (size_t)row * DM + 4 * lane + 256 * (4 * jb + j)) = w; } }
	v_pk_fma_f32 v[54:55], v[138:139], v[66:67], v[142:143]
	v_pk_fma_f32 v[56:57], v[140:141], v[62:63], v[144:145]
	global_store_dwordx4 v[64:65], v[54:57], off
	s_nop 0
	v_pk_mul_f32 v[62:63], v[118:119], v[92:93] op_sel_hi:[0,1]
	v_pk_mul_f32 v[66:67], v[118:119], v[90:91] op_sel_hi:[0,1]
	s_waitcnt vmcnt(12)
	v_pk_fma_f32 v[54:55], v[146:147], v[66:67], v[150:151]
	v_pk_fma_f32 v[56:57], v[148:149], v[62:63], v[152:153]
	global_store_dwordx4 v[64:65], v[54:57], off offset:1024
	s_nop 0
	v_pk_mul_f32 v[62:63], v[118:119], v[96:97] op_sel_hi:[0,1]
	v_pk_mul_f32 v[66:67], v[118:119], v[94:95] op_sel_hi:[0,1]
	s_waitcnt vmcnt(10)
	v_pk_fma_f32 v[54:55], v[154:155], v[66:67], v[158:159]
	v_pk_fma_f32 v[56:57], v[156:157], v[62:63], v[160:161]
	global_store_dwordx4 v[64:65], v[54:57], off offset:2048
	s_nop 0
	v_pk_mul_f32 v[62:63], v[118:119], v[100:101] op_sel_hi:[0,1]
	v_pk_mul_f32 v[66:67], v[118:119], v[98:99] op_sel_hi:[0,1]
	s_waitcnt vmcnt(8)
	v_pk_fma_f32 v[54:55], v[162:163], v[66:67], v[166:167]
	v_pk_fma_f32 v[56:57], v[164:165], v[62:63], v[168:169]
	global_store_dwordx4 v[64:65], v[54:57], off offset:3072
	s_nop 0
	v_pk_mul_f32 v[62:63], v[118:119], v[104:105] op_sel_hi:[0,1]
	v_pk_mul_f32 v[64:65], v[118:119], v[102:103] op_sel_hi:[0,1]
	v_pk_mul_f32 v[66:67], v[118:119], v[106:107] op_sel_hi:[0,1]
	s_waitcnt vmcnt(6)
	v_pk_fma_f32 v[56:57], v[172:173], v[62:63], v[176:177]
	v_add_co_u32_e32 v62, vcc, s0, v120
	v_pk_fma_f32 v[54:55], v[170:171], v[64:65], v[174:175]
	s_nop 0
	v_addc_co_u32_e32 v63, vcc, 0, v121, vcc
	global_store_dwordx4 v[62:63], v[54:57], off
	s_nop 0
	v_pk_mul_f32 v[64:65], v[118:119], v[108:109] op_sel_hi:[0,1]
	s_andn2_b64 vcc, exec, s[4:5]
	s_waitcnt vmcnt(4)
	v_pk_fma_f32 v[54:55], v[178:179], v[66:67], v[182:183]
	v_pk_fma_f32 v[56:57], v[180:181], v[64:65], v[184:185]
	global_store_dwordx4 v[62:63], v[54:57], off offset:1024
	s_nop 0
	v_pk_mul_f32 v[64:65], v[118:119], v[112:113] op_sel_hi:[0,1]
	v_pk_mul_f32 v[66:67], v[118:119], v[110:111] op_sel_hi:[0,1]
	s_waitcnt vmcnt(2)
	v_pk_fma_f32 v[54:55], v[186:187], v[66:67], v[194:195]
	v_pk_fma_f32 v[56:57], v[188:189], v[64:65], v[196:197]
	global_store_dwordx4 v[62:63], v[54:57], off offset:2048
	s_nop 0
	v_pk_mul_f32 v[64:65], v[118:119], v[114:115] op_sel_hi:[0,1]
	v_pk_mul_f32 v[66:67], v[118:119], v[116:117] op_sel_hi:[0,1]
	s_waitcnt vmcnt(0)
	v_pk_fma_f32 v[54:55], v[198:199], v[66:67], v[202:203]
	v_pk_fma_f32 v[56:57], v[200:201], v[64:65], v[204:205]
	global_store_dwordx4 v[62:63], v[54:57], off offset:3072
	s_cbranch_vccnz .LBB0_661
	s_nop 1
	v_lshl_add_u64 v[54:55], s[40:41], 0, v[192:193]
	global_load_dwordx4 v[138:141], v[54:55], off
	global_load_dwordx4 v[142:145], v[54:55], off offset:1024
	global_load_dwordx4 v[146:149], v[54:55], off offset:2048
	global_load_dwordx4 v[150:153], v[54:55], off offset:3072
	v_add_co_u32_e32 v80, vcc, s15, v54
	s_nop 1
	v_addc_co_u32_e32 v81, vcc, 0, v55, vcc
	s_movk_i32 s0, 0x1000
	s_nop 1
	v_add_co_u32_e32 v68, vcc, s0, v54
	global_load_dwordx4 v[154:157], v[80:81], off offset:-4096
	s_nop 0
	v_addc_co_u32_e32 v69, vcc, 0, v55, vcc
	global_load_dwordx4 v[158:161], v[68:69], off offset:1024
	global_load_dwordx4 v[162:165], v[68:69], off offset:2048
	s_nop 0
	global_load_dwordx4 v[166:169], v[68:69], off offset:3072
	s_movk_i32 s0, 0x3000
	global_load_dwordx4 v[170:173], v[80:81], off
	s_nop 0
	global_load_dwordx4 v[174:177], v[80:81], off offset:1024
	global_load_dwordx4 v[178:181], v[80:81], off offset:2048
	global_load_dwordx4 v[182:185], v[80:81], off offset:3072
	v_add_co_u32_e32 v80, vcc, s0, v54
	s_nop 1
	v_addc_co_u32_e32 v81, vcc, 0, v55, vcc
	global_load_dwordx4 v[186:189], v[80:81], off
	s_nop 0
	global_load_dwordx4 v[194:197], v[80:81], off offset:1024
	global_load_dwordx4 v[198:201], v[80:81], off offset:2048
	global_load_dwordx4 v[202:205], v[80:81], off offset:3072
	s_mov_b32 s4, 0xdfffe200
	s_mov_b32 s5, -1
	v_lshl_add_u64 v[72:73], v[52:53], 0, s[4:5]
	s_mov_b32 s4, 0xdfffe400
	s_mov_b32 s5, -1
	v_lshl_add_u64 v[74:75], v[52:53], 0, s[4:5]
	s_mov_b32 s4, 0xdfffe600
	s_mov_b32 s5, -1
	v_lshl_add_u64 v[76:77], v[52:53], 0, s[4:5]
	s_mov_b32 s4, 0xdfffe800
	s_nop 1
	s_mov_b32 s5, -1
	s_nop 1
	v_lshl_add_u64 v[78:79], v[52:53], 0, s[4:5]
	s_mov_b32 s4, 0xdfffea00
	s_mov_b32 s5, -1
	s_waitcnt vmcnt(15)
	v_bfe_u32 v82, v138, 16, 1
	v_bfe_u32 v84, v140, 16, 1
	v_bfe_u32 v83, v139, 16, 1
	v_bfe_u32 v85, v141, 16, 1
	s_waitcnt vmcnt(14)
	v_bfe_u32 v86, v142, 16, 1
	v_bfe_u32 v88, v144, 16, 1
	s_waitcnt vmcnt(13)
	v_bfe_u32 v90, v146, 16, 1
	v_bfe_u32 v92, v148, 16, 1
	s_waitcnt vmcnt(12)
	v_bfe_u32 v94, v150, 16, 1
	v_bfe_u32 v96, v152, 16, 1
	v_add3_u32 v56, v138, v82, s33
	v_add3_u32 v58, v140, v84, s33
	v_bfe_u32 v87, v143, 16, 1
	v_bfe_u32 v89, v145, 16, 1
	v_bfe_u32 v91, v147, 16, 1
	v_bfe_u32 v93, v149, 16, 1
	v_bfe_u32 v95, v151, 16, 1
	v_bfe_u32 v97, v153, 16, 1
	v_add3_u32 v57, v139, v83, s33
	v_add3_u32 v59, v141, v85, s33
	v_add3_u32 v60, v142, v86, s33
	v_add3_u32 v62, v144, v88, s33
	v_add3_u32 v64, v146, v90, s33
	v_add3_u32 v66, v148, v92, s33
	v_add3_u32 v68, v150, v94, s33
	v_add3_u32 v70, v152, v96, s33
	v_lshrrev_b32_e32 v56, 16, v56
	v_lshrrev_b32_e32 v58, 16, v58
	v_add3_u32 v61, v143, v87, s33
	v_add3_u32 v63, v145, v89, s33
	v_add3_u32 v65, v147, v91, s33
	v_add3_u32 v67, v149, v93, s33
	v_add3_u32 v69, v151, v95, s33
	v_add3_u32 v71, v153, v97, s33
	v_lshrrev_b32_e32 v60, 16, v60
	v_lshrrev_b32_e32 v62, 16, v62
	v_lshrrev_b32_e32 v64, 16, v64
	v_lshrrev_b32_e32 v66, 16, v66
	v_lshrrev_b32_e32 v68, 16, v68
	v_lshrrev_b32_e32 v70, 16, v70
	v_and_or_b32 v56, v57, s54, v56
	v_and_or_b32 v57, v59, s54, v58
	v_and_or_b32 v58, v61, s54, v60
	v_and_or_b32 v59, v63, s54, v62
	v_and_or_b32 v60, v65, s54, v64
	v_and_or_b32 v61, v67, s54, v66
	v_and_or_b32 v62, v69, s54, v68
	v_and_or_b32 v63, v71, s54, v70
	global_store_dwordx2 v[72:73], v[56:57], off
	global_store_dwordx2 v[74:75], v[58:59], off
	global_store_dwordx2 v[76:77], v[60:61], off
	global_store_dwordx2 v[78:79], v[62:63], off
	s_nop 0
	s_nop 0
	v_lshl_add_u64 v[72:73], v[52:53], 0, s[4:5]
	s_mov_b32 s4, 0xdfffec00
	s_mov_b32 s5, -1
	v_lshl_add_u64 v[74:75], v[52:53], 0, s[4:5]
	s_mov_b32 s4, 0xdfffee00
	s_mov_b32 s5, -1
	v_lshl_add_u64 v[76:77], v[52:53], 0, s[4:5]
	s_mov_b32 s4, 0xdffff000
	s_mov_b32 s5, -1
	v_lshl_add_u64 v[78:79], v[52:53], 0, s[4:5]
	s_mov_b32 s4, 0xdffff200
	s_mov_b32 s5, -1
	s_nop 1
	s_waitcnt vmcnt(11)
; __device__ __forceinline__ unsigned pk2(float lo, float hi) { return f2bf(lo) | (f2bf(hi) << 16); }
; __global__ void __launch_bounds__(NWAVES * 64, 2) mega_fwd(Args args) {
;     ...
;             if (g == 0) {
;                 const float* xs = args.in[1] + (size_t)row * DM;
; #pragma unroll
;                 for (int jb = 0; jb < 4; ++jb) { f32x4 t[4];
; #pragma unroll
;                     for (int j = 0; j < 4; ++j) t[j] = *(const f32x4*)(xs + 4 * lane + 256 * (4 * jb + j));
; #pragma unroll
;                     for (int j = 0; j < 4; ++j) { v2u w; w.x = pk2(t[j][0], t[j][1]); w.y = pk2(t[j][2], t[j][3]); *(v2u*)(XB + (size_t)row * DM + 4 * lane + 256 * (4 * jb + j)) = w; } }
	v_bfe_u32 v82, v154, 16, 1
	v_bfe_u32 v84, v156, 16, 1
	v_bfe_u32 v83, v155, 16, 1
	v_bfe_u32 v85, v157, 16, 1
	s_waitcnt vmcnt(10)
	v_bfe_u32 v86, v158, 16, 1
	v_bfe_u32 v88, v160, 16, 1
	s_waitcnt vmcnt(9)
	v_bfe_u32 v90, v162, 16, 1
	v_bfe_u32 v92, v164, 16, 1
	s_waitcnt vmcnt(8)
	v_bfe_u32 v94, v166, 16, 1
	v_bfe_u32 v96, v168, 16, 1
	v_add3_u32 v56, v154, v82, s33
	v_add3_u32 v58, v156, v84, s33
	v_bfe_u32 v87, v159, 16, 1
	v_bfe_u32 v89, v161, 16, 1
	v_bfe_u32 v91, v163, 16, 1
	v_bfe_u32 v93, v165, 16, 1
	v_bfe_u32 v95, v167, 16, 1
	v_bfe_u32 v97, v169, 16, 1
	v_add3_u32 v57, v155, v83, s33
	v_add3_u32 v59, v157, v85, s33
	v_add3_u32 v60, v158, v86, s33
	v_add3_u32 v62, v160, v88, s33
	v_add3_u32 v64, v162, v90, s33
	v_add3_u32 v66, v164, v92, s33
	v_add3_u32 v68, v166, v94, s33
	v_add3_u32 v70, v168, v96, s33
	v_lshrrev_b32_e32 v56, 16, v56
	v_lshrrev_b32_e32 v58, 16, v58
	v_add3_u32 v61, v159, v87, s33
	v_add3_u32 v63, v161, v89, s33
	v_add3_u32 v65, v163, v91, s33
	v_add3_u32 v67, v165, v93, s33
	v_add3_u32 v69, v167, v95, s33
	v_add3_u32 v71, v169, v97, s33
	v_lshrrev_b32_e32 v60, 16, v60
	v_lshrrev_b32_e32 v62, 16, v62
	v_lshrrev_b32_e32 v64, 16, v64
	v_lshrrev_b32_e32 v66, 16, v66
	v_lshrrev_b32_e32 v68, 16, v68
	v_lshrrev_b32_e32 v70, 16, v70
	v_and_or_b32 v56, v57, s54, v56
	v_and_or_b32 v57, v59, s54, v58
	v_and_or_b32 v58, v61, s54, v60
	v_and_or_b32 v59, v63, s54, v62
	v_and_or_b32 v60, v65, s54, v64
	v_and_or_b32 v61, v67, s54, v66
	v_and_or_b32 v62, v69, s54, v68
	v_and_or_b32 v63, v71, s54, v70
	global_store_dwordx2 v[72:73], v[56:57], off
	global_store_dwordx2 v[74:75], v[58:59], off
	global_store_dwordx2 v[76:77], v[60:61], off
	global_store_dwordx2 v[78:79], v[62:63], off
	s_nop 0
	v_lshl_add_u64 v[72:73], v[52:53], 0, s[4:5]
	s_mov_b32 s4, 0xdffff400
	s_mov_b32 s5, -1
	v_lshl_add_u64 v[74:75], v[52:53], 0, s[4:5]
	s_mov_b32 s4, 0xdffff600
	s_nop 1
	s_mov_b32 s5, -1
	s_nop 1
	v_lshl_add_u64 v[76:77], v[52:53], 0, s[4:5]
	s_mov_b32 s4, 0xdffff800
	s_mov_b32 s5, -1
	v_lshl_add_u64 v[78:79], v[52:53], 0, s[4:5]
	s_mov_b32 s4, 0xdffffa00
	s_mov_b32 s5, -1
	s_waitcnt vmcnt(7)
	v_bfe_u32 v54, v170, 16, 1
	v_bfe_u32 v82, v172, 16, 1
	v_bfe_u32 v55, v171, 16, 1
	v_bfe_u32 v83, v173, 16, 1
	s_waitcnt vmcnt(6)
	v_bfe_u32 v84, v174, 16, 1
	v_bfe_u32 v86, v176, 16, 1
	s_waitcnt vmcnt(5)
	v_bfe_u32 v88, v178, 16, 1
	v_bfe_u32 v90, v180, 16, 1
	s_waitcnt vmcnt(4)
	v_bfe_u32 v92, v182, 16, 1
	v_bfe_u32 v94, v184, 16, 1
	v_add3_u32 v54, v170, v54, s33
	v_add3_u32 v56, v172, v82, s33
	v_bfe_u32 v85, v175, 16, 1
	v_bfe_u32 v87, v177, 16, 1
	v_bfe_u32 v89, v179, 16, 1
	v_bfe_u32 v91, v181, 16, 1
	v_bfe_u32 v93, v183, 16, 1
	v_bfe_u32 v95, v185, 16, 1
	v_add3_u32 v55, v171, v55, s33
	v_add3_u32 v57, v173, v83, s33
	v_add3_u32 v58, v174, v84, s33
	v_add3_u32 v60, v176, v86, s33
	v_add3_u32 v62, v178, v88, s33
	v_add3_u32 v64, v180, v90, s33
	v_add3_u32 v66, v182, v92, s33
	v_add3_u32 v68, v184, v94, s33
	v_lshrrev_b32_e32 v54, 16, v54
	v_lshrrev_b32_e32 v56, 16, v56
	v_add3_u32 v59, v175, v85, s33
	v_add3_u32 v61, v177, v87, s33
	v_add3_u32 v63, v179, v89, s33
	v_add3_u32 v65, v181, v91, s33
	v_add3_u32 v67, v183, v93, s33
	v_add3_u32 v69, v185, v95, s33
	v_lshrrev_b32_e32 v58, 16, v58
	v_lshrrev_b32_e32 v60, 16, v60
	v_lshrrev_b32_e32 v62, 16, v62
	v_lshrrev_b32_e32 v64, 16, v64
	v_lshrrev_b32_e32 v66, 16, v66
	v_lshrrev_b32_e32 v68, 16, v68
	v_and_or_b32 v54, v55, s54, v54
	v_and_or_b32 v55, v57, s54, v56
	v_and_or_b32 v56, v59, s54, v58
	v_and_or_b32 v57, v61, s54, v60
	v_and_or_b32 v58, v63, s54, v62
	v_and_or_b32 v59, v65, s54, v64
	v_and_or_b32 v60, v67, s54, v66
	v_and_or_b32 v61, v69, s54, v68
	global_store_dwordx2 v[72:73], v[54:55], off
	global_store_dwordx2 v[74:75], v[56:57], off
	global_store_dwordx2 v[76:77], v[58:59], off
	global_store_dwordx2 v[78:79], v[60:61], off
	s_nop 0
	v_lshl_add_u64 v[70:71], v[52:53], 0, s[4:5]
	s_mov_b32 s4, 0xdffffc00
	s_mov_b32 s5, -1
	v_lshl_add_u64 v[72:73], v[52:53], 0, s[4:5]
	s_mov_b32 s4, 0xdffffe00
	s_mov_b32 s5, -1
	v_lshl_add_u64 v[74:75], v[52:53], 0, s[4:5]
	s_brev_b32 s4, 7
	s_mov_b32 s5, -1
	v_lshl_add_u64 v[76:77], v[52:53], 0, s[4:5]
	s_waitcnt vmcnt(3)
	v_bfe_u32 v78, v186, 16, 1
	v_bfe_u32 v80, v188, 16, 1
	v_bfe_u32 v79, v187, 16, 1
	v_bfe_u32 v81, v189, 16, 1
	s_waitcnt vmcnt(2)
	v_bfe_u32 v82, v194, 16, 1
	v_bfe_u32 v84, v196, 16, 1
	s_waitcnt vmcnt(1)
	v_bfe_u32 v86, v198, 16, 1
	v_bfe_u32 v88, v200, 16, 1
	s_waitcnt vmcnt(0)
	v_bfe_u32 v90, v202, 16, 1
	v_bfe_u32 v92, v204, 16, 1
	v_add3_u32 v54, v186, v78, s33
	v_add3_u32 v56, v188, v80, s33
	v_bfe_u32 v83, v195, 16, 1
	v_bfe_u32 v85, v197, 16, 1
	v_bfe_u32 v87, v199, 16, 1
	v_bfe_u32 v89, v201, 16, 1
	v_bfe_u32 v91, v203, 16, 1
	v_bfe_u32 v93, v205, 16, 1
	v_add3_u32 v55, v187, v79, s33
	v_add3_u32 v57, v189, v81, s33
	v_add3_u32 v58, v194, v82, s33
	v_add3_u32 v60, v196, v84, s33
	v_add3_u32 v62, v198, v86, s33
	v_add3_u32 v64, v200, v88, s33
	v_add3_u32 v66, v202, v90, s33
	v_add3_u32 v68, v204, v92, s33
	v_lshrrev_b32_e32 v54, 16, v54
	v_lshrrev_b32_e32 v56, 16, v56
	v_add3_u32 v59, v195, v83, s33
	v_add3_u32 v61, v197, v85, s33
	v_add3_u32 v63, v199, v87, s33
	v_add3_u32 v65, v201, v89, s33
	v_add3_u32 v67, v203, v91, s33
	v_add3_u32 v69, v205, v93, s33
	v_lshrrev_b32_e32 v58, 16, v58
	v_lshrrev_b32_e32 v60, 16, v60
	v_lshrrev_b32_e32 v62, 16, v62
	v_lshrrev_b32_e32 v64, 16, v64
	v_lshrrev_b32_e32 v66, 16, v66
	v_lshrrev_b32_e32 v68, 16, v68
	v_and_or_b32 v54, v55, s54, v54
	v_and_or_b32 v55, v57, s54, v56
	v_and_or_b32 v56, v59, s54, v58
	v_and_or_b32 v57, v61, s54, v60
	v_and_or_b32 v58, v63, s54, v62
	v_and_or_b32 v59, v65, s54, v64
	v_and_or_b32 v60, v67, s54, v66
	v_and_or_b32 v61, v69, s54, v68
	global_store_dwordx2 v[70:71], v[54:55], off
	global_store_dwordx2 v[72:73], v[56:57], off
	global_store_dwordx2 v[74:75], v[58:59], off
	global_store_dwordx2 v[76:77], v[60:61], off
	s_branch .LBB0_661
